# s8 + LRU next-block conv inputs loaded straight into the window registers (no staging copies) + cross-attention epilogue gate fragments prefetched at phase start
# speedup vs baseline: 1.0198x; 1.0019x over previous
.LBB0_208:
	s_waitcnt vmcnt(0)
	v_lshlrev_b32_e32 v2, 1, v111
	v_lshl_add_u64 v[14:15], v[82:83], 0, v[2:3]
	global_load_dwordx2 v[20:21], v[14:15], off offset:3072
	v_readlane_b32 s8, v244, 0
	v_lshlrev_b32_e32 v18, 2, v111
	v_readlane_b32 s12, v244, 4
	v_readlane_b32 s13, v244, 5
	v_mov_b32_e32 v16, v110
	s_nop 1
	v_permlane16_swap_b32 v16, v110
	v_readlane_b32 s4, v244, 57
	v_lshlrev_b64 v[12:13], 11, v[80:81]
	v_readlane_b32 s6, v244, 59
	v_readlane_b32 s7, v244, 60
	global_load_dwordx4 v[8:11], v18, s[12:13] offset:2048
	global_load_dwordx2 v[46:47], v[14:15], off offset:3104
	global_load_dwordx2 v[52:53], v[14:15], off offset:3136
	global_load_dwordx2 v[54:55], v[14:15], off offset:3168
	global_load_dwordx4 v[56:59], v18, s[12:13] offset:2112
	global_load_dwordx4 v[60:63], v18, s[12:13] offset:2176
	global_load_dwordx4 v[64:67], v18, s[12:13] offset:2240
	global_load_dwordx2 v[68:69], v[14:15], off offset:3200
	global_load_dwordx4 v[70:73], v18, s[12:13] offset:2304
	global_load_dwordx2 v[74:75], v[14:15], off offset:3232
	global_load_dwordx2 v[76:77], v[14:15], off offset:3264
	global_load_dwordx2 v[78:79], v[14:15], off offset:3296
	global_load_dwordx4 v[84:87], v18, s[12:13] offset:2368
	global_load_dwordx4 v[88:91], v18, s[12:13] offset:2432
	global_load_dwordx4 v[92:95], v18, s[12:13] offset:2496
	global_load_dwordx2 v[96:97], v[14:15], off offset:3328
	global_load_dwordx4 v[98:101], v18, s[12:13] offset:2560
	global_load_dwordx2 v[102:103], v[14:15], off offset:3360
	global_load_dwordx2 v[104:105], v[14:15], off offset:3392
	global_load_dwordx2 v[106:107], v[14:15], off offset:3424
	global_load_dwordx4 v[116:119], v18, s[12:13] offset:2624
	global_load_dwordx4 v[120:123], v18, s[12:13] offset:2688
	global_load_dwordx4 v[124:127], v18, s[12:13] offset:2752
	global_load_dwordx2 v[132:133], v[14:15], off offset:3456
	global_load_dwordx4 v[134:137], v18, s[12:13] offset:2816
	global_load_dwordx2 v[138:139], v[14:15], off offset:3488
	global_load_dwordx2 v[140:141], v[14:15], off offset:3520
	global_load_dwordx2 v[142:143], v[14:15], off offset:3552
	global_load_dwordx4 v[144:147], v18, s[12:13] offset:2880
	global_load_dwordx4 v[148:151], v18, s[12:13] offset:2944
	global_load_dwordx4 v[152:155], v18, s[12:13] offset:3008
	v_readlane_b32 s24, v243, 8
	v_readlane_b32 s26, v244, 50
	v_readlane_b32 s27, v244, 51
	v_readlane_b32 s28, v243, 30
	v_readlane_b32 s30, v243, 5
	v_readlane_b32 s31, v243, 6
	v_lshrrev_b32_e32 v108, 1, v0
	v_and_b32_e32 v129, 1, v0
	v_and_b32_e32 v168, 15, v0
	v_lshrrev_b32_e32 v169, 6, v0
	v_lshl_add_u32 v108, s24, 8, v108
	v_lshlrev_b32_e32 v129, 6, v129
	v_or_b32_e32 v168, s28, v168
	v_lshl_add_u32 v108, v108, 10, v129
	v_lshl_add_u32 v168, v169, 4, v168
	v_bfe_u32 v169, v0, 4, 2
	v_mul_u32_u24_e32 v168, 0x1200, v168
	v_lshl_add_u32 v168, v169, 4, v168
	global_load_dwordx4 v[156:159], v108, s[26:27] offset:48
	global_load_dwordx4 v[160:163], v108, s[26:27] offset:32
	global_load_dwordx4 v[164:167], v108, s[26:27] offset:16
	global_load_dwordx4 v[172:175], v108, s[26:27]
	global_load_dwordx4 v[176:179], v108, s[26:27] offset:512
	global_load_dwordx4 v[196:199], v108, s[26:27] offset:528
	global_load_dwordx4 v[200:203], v108, s[26:27] offset:544
	global_load_dwordx4 v[204:207], v108, s[26:27] offset:560
	global_load_dwordx4 v[208:211], v168, s[30:31] offset:3584
	global_load_dwordx4 v[212:215], v168, s[30:31] offset:3648
	s_waitcnt lgkmcnt(0)
	v_add_f32_e32 v19, v110, v16
	v_mov_b32_e32 v28, v19
	s_nop 1
	v_permlane32_swap_b32 v28, v19
	s_mov_b64 s[0:1], 0xdde0400
	v_lshl_add_u64 v[12:13], s[6:7], 0, v[12:13]
	v_lshl_add_u64 v[12:13], v[12:13], 0, s[0:1]
	s_mov_b32 s0, 0x800000
	s_waitcnt lgkmcnt(0)
	v_add_f32_e32 v19, v19, v28
	v_fmamk_f32 v19, v19, 0x3b800000, v180
	v_mul_f32_e32 v28, 0x4b800000, v19
	v_cmp_gt_f32_e32 vcc, s0, v19
	ds_read2_b64 v[4:7], v109 offset1:4
	v_cndmask_b32_e32 v19, v19, v28, vcc
	v_rsq_f32_e32 v19, v19
	v_lshl_add_u64 v[26:27], v[12:13], 0, v[2:3]
	s_waitcnt lgkmcnt(0)
	v_lshlrev_b32_e32 v29, 16, v4
	v_and_b32_e32 v31, 0xffff0000, v4
	v_mul_f32_e32 v4, 0x45800000, v19
	v_lshlrev_b32_e32 v33, 16, v5
	v_and_b32_e32 v35, 0xffff0000, v5
	v_cndmask_b32_e32 v5, v19, v4, vcc
	v_mov_b32_e32 v38, v5
	v_mov_b32_e32 v40, v5
	v_mov_b32_e32 v42, v5
	v_readlane_b32 s88, v243, 5
	v_readlane_b32 s20, v243, 30
	v_readlane_b32 s89, v243, 6
	v_readlane_b32 s0, v243, 8
	v_mov_b32_e32 v45, v3
	v_mov_b32_e32 v115, v3
	v_readlane_b32 s2, v244, 62
	v_readlane_b32 s10, v244, 2
	v_readlane_b32 s11, v244, 3
	v_mov_b32_e32 v51, v3
	v_readlane_b32 s9, v244, 1
	v_readlane_b32 s3, v244, 63
	v_readlane_b32 s14, v244, 6
	v_readlane_b32 s15, v244, 7
	v_readlane_b32 s5, v244, 58
	v_readlane_b32 s86, v243, 3
	v_readlane_b32 s22, v243, 28
	v_mov_b32_e32 v130, 0
	s_mov_b64 s[4:5], 0
	v_readlane_b32 s58, v243, 2
	v_readlane_b32 s87, v243, 4
	s_movk_i32 s84, 0x7f
	v_readlane_b32 s23, v243, 29
	v_readlane_b32 s21, v243, 31
	s_waitcnt vmcnt(41)
	v_lshlrev_b32_e32 v28, 16, v20
	v_mul_f32_e32 v4, 0xbfb8aa3b, v28
	v_exp_f32_e32 v4, v4
	v_and_b32_e32 v30, 0xffff0000, v20
	v_mul_f32_e32 v19, 0xbfb8aa3b, v30
	v_exp_f32_e32 v19, v19
	v_add_f32_e32 v4, 1.0, v4
	v_rcp_f32_e32 v4, v4
	v_lshlrev_b32_e32 v32, 16, v21
	v_and_b32_e32 v34, 0xffff0000, v21
	v_mul_f32_e32 v20, 0xbfb8aa3b, v32
	v_mul_f32_e32 v21, 0xbfb8aa3b, v34
	v_exp_f32_e32 v36, v20
	v_add_f32_e32 v19, 1.0, v19
	v_exp_f32_e32 v37, v21
	v_pk_mul_f32 v[20:21], v[4:5], v[28:29]
	v_rcp_f32_e32 v4, v19
	v_add_f32_e32 v19, 1.0, v36
	s_waitcnt vmcnt(40)
	v_mul_f32_e32 v8, v8, v21
	v_add_f32_e32 v36, 1.0, v37
	v_pk_mul_f32 v[28:29], v[4:5], v[30:31]
	v_rcp_f32_e32 v4, v19
	v_mul_f32_e32 v19, v20, v8
	v_mul_f32_e32 v8, v9, v29
	v_mul_f32_e32 v20, v28, v8
	v_pk_mul_f32 v[8:9], v[4:5], v[32:33]
	v_rcp_f32_e32 v4, v36
	v_mul_f32_e32 v9, v10, v9
	v_mul_f32_e32 v10, v8, v9
	v_cvt_pk_bf16_f32 v20, v19, v20
	v_pk_mul_f32 v[8:9], v[4:5], v[34:35]
	v_lshlrev_b32_e32 v28, 16, v7
	v_mul_f32_e32 v4, v11, v9
	v_mul_f32_e32 v4, v8, v4
	v_cvt_pk_bf16_f32 v21, v10, v4
	global_store_dwordx2 v[26:27], v[20:21], off
	v_and_b32_e32 v30, 0xffff0000, v7
	s_waitcnt vmcnt(40)
	v_lshlrev_b32_e32 v27, 16, v46
	v_and_b32_e32 v7, 0xffff0000, v46
	v_lshlrev_b32_e32 v29, 16, v47
	v_and_b32_e32 v31, 0xffff0000, v47
	v_mul_f32_e32 v4, 0xbfb8aa3b, v27
	v_mul_f32_e32 v19, 0xbfb8aa3b, v7
	v_mul_f32_e32 v22, 0xbfb8aa3b, v29
	v_mul_f32_e32 v23, 0xbfb8aa3b, v31
	v_exp_f32_e32 v4, v4
	v_exp_f32_e32 v19, v19
	v_exp_f32_e32 v22, v22
	v_exp_f32_e32 v23, v23
	v_add_f32_e32 v4, 1.0, v4
	v_add_f32_e32 v19, 1.0, v19
	v_add_f32_e32 v22, 1.0, v22
	v_add_f32_e32 v23, 1.0, v23
	v_rcp_f32_e32 v33, v4
	v_rcp_f32_e32 v35, v19
	v_rcp_f32_e32 v37, v22
	v_rcp_f32_e32 v39, v23
	v_lshlrev_b32_e32 v26, 16, v6
	v_and_b32_e32 v6, 0xffff0000, v6
	v_mov_b32_e32 v32, v5
	v_mov_b32_e32 v34, v5
	v_mov_b32_e32 v36, v5
	v_pk_mul_f32 v[22:23], v[32:33], v[26:27]
	v_pk_mul_f32 v[6:7], v[34:35], v[6:7]
	v_pk_mul_f32 v[26:27], v[36:37], v[28:29]
	v_mov_b32_e32 v21, v3
	v_or_b32_e32 v20, 32, v2
	v_pk_mul_f32 v[28:29], v[38:39], v[30:31]
	v_lshl_add_u64 v[20:21], v[12:13], 0, v[20:21]
	s_waitcnt vmcnt(39)
	v_and_b32_e32 v31, 0xffff0000, v53
	s_waitcnt vmcnt(37)
	v_mul_f32_e32 v4, v56, v22
	v_mul_f32_e32 v6, v57, v6
	v_mul_f32_e32 v8, v58, v26
	v_mul_f32_e32 v9, v59, v28
	v_mul_f32_e32 v6, v6, v7
	v_mul_f32_e32 v7, v8, v27
	v_mul_f32_e32 v4, v4, v23
	v_mul_f32_e32 v8, v9, v29
	v_cvt_pk_bf16_f32 v6, v4, v6
	v_cvt_pk_bf16_f32 v7, v7, v8
	global_store_dwordx2 v[20:21], v[6:7], off
	ds_read2_b64 v[20:23], v109 offset0:8 offset1:12
	v_lshlrev_b32_e32 v27, 16, v52
	v_lshlrev_b32_e32 v29, 16, v53
	v_mul_f32_e32 v4, 0xbfb8aa3b, v27
	v_mul_f32_e32 v25, 0xbfb8aa3b, v31
	s_waitcnt lgkmcnt(0)
	v_lshlrev_b32_e32 v28, 16, v21
	v_and_b32_e32 v30, 0xffff0000, v21
	v_and_b32_e32 v21, 0xffff0000, v52
	v_mul_f32_e32 v19, 0xbfb8aa3b, v21
	v_mul_f32_e32 v24, 0xbfb8aa3b, v29
	v_exp_f32_e32 v4, v4
	v_exp_f32_e32 v19, v19
	v_exp_f32_e32 v24, v24
	v_exp_f32_e32 v25, v25
	v_add_f32_e32 v4, 1.0, v4
	v_add_f32_e32 v19, 1.0, v19
	v_add_f32_e32 v24, 1.0, v24
	v_add_f32_e32 v25, 1.0, v25
	v_rcp_f32_e32 v33, v4
	v_rcp_f32_e32 v35, v19
	v_rcp_f32_e32 v37, v24
	v_rcp_f32_e32 v39, v25
	v_lshlrev_b32_e32 v26, 16, v20
	v_and_b32_e32 v20, 0xffff0000, v20
	v_pk_mul_f32 v[24:25], v[32:33], v[26:27]
	v_pk_mul_f32 v[20:21], v[34:35], v[20:21]
	v_pk_mul_f32 v[26:27], v[36:37], v[28:29]
	v_mov_b32_e32 v11, v3
	v_or_b32_e32 v10, 64, v2
	v_pk_mul_f32 v[28:29], v[38:39], v[30:31]
	v_lshl_add_u64 v[10:11], v[12:13], 0, v[10:11]
	v_mov_b32_e32 v30, v5
	s_waitcnt vmcnt(37)
	v_mul_f32_e32 v4, v60, v24
	v_mul_f32_e32 v6, v61, v20
	v_mul_f32_e32 v7, v62, v26
	v_mul_f32_e32 v8, v63, v28
	v_mul_f32_e32 v6, v6, v21
	v_mul_f32_e32 v7, v7, v27
	v_mul_f32_e32 v4, v4, v25
	v_mul_f32_e32 v8, v8, v29
	v_cvt_pk_bf16_f32 v6, v4, v6
	v_cvt_pk_bf16_f32 v7, v7, v8
	global_store_dwordx2 v[10:11], v[6:7], off
	v_lshlrev_b32_e32 v26, 16, v23
	v_and_b32_e32 v28, 0xffff0000, v23
	v_lshlrev_b32_e32 v21, 16, v54
	v_and_b32_e32 v23, 0xffff0000, v54
	v_lshlrev_b32_e32 v27, 16, v55
	v_and_b32_e32 v29, 0xffff0000, v55
	v_mul_f32_e32 v4, 0xbfb8aa3b, v21
	v_mul_f32_e32 v16, 0xbfb8aa3b, v23
	v_mul_f32_e32 v17, 0xbfb8aa3b, v27
	v_mul_f32_e32 v19, 0xbfb8aa3b, v29
	v_exp_f32_e32 v4, v4
	v_exp_f32_e32 v16, v16
	v_exp_f32_e32 v17, v17
	v_exp_f32_e32 v19, v19
	v_add_f32_e32 v4, 1.0, v4
	v_add_f32_e32 v16, 1.0, v16
	v_add_f32_e32 v17, 1.0, v17
	v_add_f32_e32 v19, 1.0, v19
	v_rcp_f32_e32 v31, v4
	v_rcp_f32_e32 v33, v16
	v_rcp_f32_e32 v35, v17
	v_rcp_f32_e32 v37, v19
	v_lshlrev_b32_e32 v20, 16, v22
	v_and_b32_e32 v22, 0xffff0000, v22
	v_pk_mul_f32 v[16:17], v[30:31], v[20:21]
	v_pk_mul_f32 v[20:21], v[32:33], v[22:23]
	v_pk_mul_f32 v[22:23], v[34:35], v[26:27]
	v_mov_b32_e32 v11, v3
	v_or_b32_e32 v10, 0x60, v2
	v_pk_mul_f32 v[26:27], v[36:37], v[28:29]
	v_lshl_add_u64 v[10:11], v[12:13], 0, v[10:11]
	s_waitcnt vmcnt(37)
	v_mul_f32_e32 v4, v64, v16
	v_mul_f32_e32 v6, v65, v20
	v_mul_f32_e32 v7, v66, v22
	v_mul_f32_e32 v8, v67, v26
	v_mul_f32_e32 v6, v6, v21
	v_mul_f32_e32 v7, v7, v23
	v_mul_f32_e32 v4, v4, v17
	v_mul_f32_e32 v8, v8, v27
	v_cvt_pk_bf16_f32 v6, v4, v6
	v_cvt_pk_bf16_f32 v7, v7, v8
	global_store_dwordx2 v[10:11], v[6:7], off
	ds_read2_b64 v[20:23], v109 offset0:16 offset1:20
	s_waitcnt vmcnt(37)
	v_lshlrev_b32_e32 v31, 16, v68
	v_lshlrev_b32_e32 v33, 16, v69
	v_and_b32_e32 v35, 0xffff0000, v69
	s_waitcnt lgkmcnt(0)
	v_lshlrev_b32_e32 v32, 16, v21
	v_and_b32_e32 v34, 0xffff0000, v21
	v_and_b32_e32 v21, 0xffff0000, v68
	v_mul_f32_e32 v4, 0xbfb8aa3b, v31
	v_mul_f32_e32 v19, 0xbfb8aa3b, v21
	v_mul_f32_e32 v24, 0xbfb8aa3b, v33
	v_mul_f32_e32 v25, 0xbfb8aa3b, v35
	v_exp_f32_e32 v4, v4
	v_exp_f32_e32 v19, v19
	v_exp_f32_e32 v24, v24
	v_exp_f32_e32 v25, v25
	v_add_f32_e32 v4, 1.0, v4
	v_add_f32_e32 v19, 1.0, v19
	v_add_f32_e32 v24, 1.0, v24
	v_add_f32_e32 v25, 1.0, v25
	v_rcp_f32_e32 v37, v4
	v_rcp_f32_e32 v39, v19
	v_rcp_f32_e32 v41, v24
	v_rcp_f32_e32 v43, v25
	v_lshlrev_b32_e32 v30, 16, v20
	v_and_b32_e32 v20, 0xffff0000, v20
	v_pk_mul_f32 v[24:25], v[36:37], v[30:31]
	v_pk_mul_f32 v[20:21], v[38:39], v[20:21]
	v_pk_mul_f32 v[30:31], v[40:41], v[32:33]
	v_mov_b32_e32 v17, v3
	v_or_b32_e32 v16, 0x80, v2
	v_pk_mul_f32 v[32:33], v[42:43], v[34:35]
	v_lshl_add_u64 v[16:17], v[12:13], 0, v[16:17]
	v_mov_b32_e32 v34, v5
	s_waitcnt vmcnt(36)
	v_mul_f32_e32 v4, v70, v24
	v_mul_f32_e32 v8, v71, v20
	v_mul_f32_e32 v9, v72, v30
	v_mul_f32_e32 v10, v73, v32
	v_mul_f32_e32 v8, v8, v21
	v_mul_f32_e32 v9, v9, v31
	v_mul_f32_e32 v4, v4, v25
	v_mul_f32_e32 v10, v10, v33
	v_cvt_pk_bf16_f32 v8, v4, v8
	v_cvt_pk_bf16_f32 v9, v9, v10
	global_store_dwordx2 v[16:17], v[8:9], off
	v_lshlrev_b32_e32 v24, 16, v23
	v_and_b32_e32 v30, 0xffff0000, v23
	s_waitcnt vmcnt(36)
	v_lshlrev_b32_e32 v21, 16, v74
	v_and_b32_e32 v23, 0xffff0000, v74
	v_lshlrev_b32_e32 v25, 16, v75
	v_and_b32_e32 v31, 0xffff0000, v75
	v_mul_f32_e32 v4, 0xbfb8aa3b, v21
	v_mul_f32_e32 v19, 0xbfb8aa3b, v23
	v_mul_f32_e32 v26, 0xbfb8aa3b, v25
	v_mul_f32_e32 v27, 0xbfb8aa3b, v31
	v_exp_f32_e32 v4, v4
	v_exp_f32_e32 v19, v19
	v_exp_f32_e32 v26, v26
	v_exp_f32_e32 v27, v27
	v_add_f32_e32 v4, 1.0, v4
	v_add_f32_e32 v19, 1.0, v19
	v_add_f32_e32 v26, 1.0, v26
	v_add_f32_e32 v27, 1.0, v27
	v_rcp_f32_e32 v33, v4
	v_rcp_f32_e32 v35, v19
	v_rcp_f32_e32 v37, v26
	v_rcp_f32_e32 v39, v27
	v_lshlrev_b32_e32 v20, 16, v22
	v_and_b32_e32 v22, 0xffff0000, v22
	v_mov_b32_e32 v32, v5
	v_pk_mul_f32 v[20:21], v[32:33], v[20:21]
	v_pk_mul_f32 v[22:23], v[34:35], v[22:23]
	v_pk_mul_f32 v[24:25], v[36:37], v[24:25]
	v_mov_b32_e32 v17, v3
	v_or_b32_e32 v16, 0xa0, v2
	v_pk_mul_f32 v[26:27], v[38:39], v[30:31]
	v_lshl_add_u64 v[16:17], v[12:13], 0, v[16:17]
	s_waitcnt vmcnt(35)
	v_and_b32_e32 v31, 0xffff0000, v77
	s_waitcnt vmcnt(33)
	v_mul_f32_e32 v4, v84, v20
	v_mul_f32_e32 v8, v85, v22
	v_mul_f32_e32 v9, v86, v24
	v_mul_f32_e32 v10, v87, v26
	v_mul_f32_e32 v8, v8, v23
	v_mul_f32_e32 v9, v9, v25
	v_mul_f32_e32 v4, v4, v21
	v_mul_f32_e32 v10, v10, v27
	v_cvt_pk_bf16_f32 v8, v4, v8
	v_cvt_pk_bf16_f32 v9, v9, v10
	global_store_dwordx2 v[16:17], v[8:9], off
	ds_read2_b64 v[20:23], v109 offset0:24 offset1:28
	v_lshlrev_b32_e32 v25, 16, v76
	v_lshlrev_b32_e32 v27, 16, v77
	v_mul_f32_e32 v4, 0xbfb8aa3b, v25
	v_mul_f32_e32 v29, 0xbfb8aa3b, v31
	s_waitcnt lgkmcnt(0)
	v_lshlrev_b32_e32 v26, 16, v21
	v_and_b32_e32 v30, 0xffff0000, v21
	v_and_b32_e32 v21, 0xffff0000, v76
	v_mul_f32_e32 v19, 0xbfb8aa3b, v21
	v_mul_f32_e32 v28, 0xbfb8aa3b, v27
	v_exp_f32_e32 v4, v4
	v_exp_f32_e32 v19, v19
	v_exp_f32_e32 v28, v28
	v_exp_f32_e32 v29, v29
	v_add_f32_e32 v4, 1.0, v4
	v_add_f32_e32 v19, 1.0, v19
	v_add_f32_e32 v28, 1.0, v28
	v_add_f32_e32 v29, 1.0, v29
	v_rcp_f32_e32 v33, v4
	v_rcp_f32_e32 v35, v19
	v_rcp_f32_e32 v37, v28
	v_rcp_f32_e32 v39, v29
	v_lshlrev_b32_e32 v24, 16, v20
	v_and_b32_e32 v20, 0xffff0000, v20
	v_pk_mul_f32 v[24:25], v[32:33], v[24:25]
	v_pk_mul_f32 v[20:21], v[34:35], v[20:21]
	v_pk_mul_f32 v[26:27], v[36:37], v[26:27]
	v_mov_b32_e32 v17, v3
	v_or_b32_e32 v16, 0xc0, v2
	v_pk_mul_f32 v[28:29], v[38:39], v[30:31]
	v_lshl_add_u64 v[16:17], v[12:13], 0, v[16:17]
	v_mov_b32_e32 v30, v5
	s_waitcnt vmcnt(33)
	v_mul_f32_e32 v4, v88, v24
	v_mul_f32_e32 v8, v89, v20
	v_mul_f32_e32 v9, v90, v26
	v_mul_f32_e32 v10, v91, v28
	v_mul_f32_e32 v8, v8, v21
	v_mul_f32_e32 v9, v9, v27
	v_mul_f32_e32 v4, v4, v25
	v_mul_f32_e32 v10, v10, v29
	v_cvt_pk_bf16_f32 v8, v4, v8
	v_cvt_pk_bf16_f32 v9, v9, v10
	global_store_dwordx2 v[16:17], v[8:9], off
	v_lshlrev_b32_e32 v26, 16, v23
	v_and_b32_e32 v28, 0xffff0000, v23
	v_lshlrev_b32_e32 v21, 16, v78
	v_and_b32_e32 v23, 0xffff0000, v78
	v_lshlrev_b32_e32 v27, 16, v79
	v_and_b32_e32 v29, 0xffff0000, v79
	v_mul_f32_e32 v4, 0xbfb8aa3b, v21
	v_mul_f32_e32 v6, 0xbfb8aa3b, v23
	v_mul_f32_e32 v7, 0xbfb8aa3b, v27
	v_mul_f32_e32 v19, 0xbfb8aa3b, v29
	v_exp_f32_e32 v4, v4
	v_exp_f32_e32 v6, v6
	v_exp_f32_e32 v7, v7
	v_exp_f32_e32 v19, v19
	v_add_f32_e32 v4, 1.0, v4
	v_add_f32_e32 v6, 1.0, v6
	v_add_f32_e32 v7, 1.0, v7
	v_add_f32_e32 v19, 1.0, v19
	v_rcp_f32_e32 v31, v4
	v_rcp_f32_e32 v33, v6
	v_rcp_f32_e32 v35, v7
	v_rcp_f32_e32 v37, v19
	v_lshlrev_b32_e32 v20, 16, v22
	v_and_b32_e32 v22, 0xffff0000, v22
	v_pk_mul_f32 v[6:7], v[30:31], v[20:21]
	v_pk_mul_f32 v[20:21], v[32:33], v[22:23]
	v_pk_mul_f32 v[22:23], v[34:35], v[26:27]
	v_mov_b32_e32 v17, v3
	v_or_b32_e32 v16, 0xe0, v2
	v_pk_mul_f32 v[26:27], v[36:37], v[28:29]
	v_lshl_add_u64 v[16:17], v[12:13], 0, v[16:17]
	s_waitcnt vmcnt(33)
	v_mul_f32_e32 v4, v92, v6
	v_mul_f32_e32 v6, v93, v20
	v_mul_f32_e32 v8, v94, v22
	v_mul_f32_e32 v9, v95, v26
	v_mul_f32_e32 v4, v4, v7
	v_mul_f32_e32 v6, v6, v21
	v_mul_f32_e32 v7, v8, v23
	v_mul_f32_e32 v8, v9, v27
	v_cvt_pk_bf16_f32 v6, v4, v6
	v_cvt_pk_bf16_f32 v7, v7, v8
	global_store_dwordx2 v[16:17], v[6:7], off
	ds_read2_b64 v[20:23], v109 offset0:32 offset1:36
	s_waitcnt vmcnt(33)
	v_lshlrev_b32_e32 v31, 16, v96
	v_lshlrev_b32_e32 v33, 16, v97
	v_and_b32_e32 v35, 0xffff0000, v97
	s_waitcnt lgkmcnt(0)
	v_lshlrev_b32_e32 v32, 16, v21
	v_and_b32_e32 v34, 0xffff0000, v21
	v_and_b32_e32 v21, 0xffff0000, v96
	v_mul_f32_e32 v4, 0xbfb8aa3b, v31
	v_mul_f32_e32 v19, 0xbfb8aa3b, v21
	v_mul_f32_e32 v24, 0xbfb8aa3b, v33
	v_mul_f32_e32 v25, 0xbfb8aa3b, v35
	v_exp_f32_e32 v4, v4
	v_exp_f32_e32 v19, v19
	v_exp_f32_e32 v24, v24
	v_exp_f32_e32 v25, v25
	v_add_f32_e32 v4, 1.0, v4
	v_add_f32_e32 v19, 1.0, v19
	v_add_f32_e32 v24, 1.0, v24
	v_add_f32_e32 v25, 1.0, v25
	v_rcp_f32_e32 v37, v4
	v_rcp_f32_e32 v39, v19
	v_rcp_f32_e32 v41, v24
	v_rcp_f32_e32 v43, v25
	v_lshlrev_b32_e32 v30, 16, v20
	v_and_b32_e32 v20, 0xffff0000, v20
	v_pk_mul_f32 v[24:25], v[36:37], v[30:31]
	v_pk_mul_f32 v[20:21], v[38:39], v[20:21]
	v_pk_mul_f32 v[30:31], v[40:41], v[32:33]
	v_mov_b32_e32 v17, v3
	v_or_b32_e32 v16, 0x100, v2
	v_pk_mul_f32 v[32:33], v[42:43], v[34:35]
	v_lshl_add_u64 v[16:17], v[12:13], 0, v[16:17]
	v_mov_b32_e32 v34, v5
	s_waitcnt vmcnt(32)
	v_mul_f32_e32 v4, v98, v24
	v_mul_f32_e32 v8, v99, v20
	v_mul_f32_e32 v9, v100, v30
	v_mul_f32_e32 v10, v101, v32
	v_mul_f32_e32 v8, v8, v21
	v_mul_f32_e32 v9, v9, v31
	v_mul_f32_e32 v4, v4, v25
	v_mul_f32_e32 v10, v10, v33
	v_cvt_pk_bf16_f32 v8, v4, v8
	v_cvt_pk_bf16_f32 v9, v9, v10
	global_store_dwordx2 v[16:17], v[8:9], off
	v_lshlrev_b32_e32 v24, 16, v23
	v_and_b32_e32 v30, 0xffff0000, v23
	s_waitcnt vmcnt(32)
	v_lshlrev_b32_e32 v21, 16, v102
	v_and_b32_e32 v23, 0xffff0000, v102
	v_lshlrev_b32_e32 v25, 16, v103
	v_and_b32_e32 v31, 0xffff0000, v103
	v_mul_f32_e32 v4, 0xbfb8aa3b, v21
	v_mul_f32_e32 v19, 0xbfb8aa3b, v23
	v_mul_f32_e32 v26, 0xbfb8aa3b, v25
	v_mul_f32_e32 v27, 0xbfb8aa3b, v31
	v_exp_f32_e32 v4, v4
	v_exp_f32_e32 v19, v19
	v_exp_f32_e32 v26, v26
	v_exp_f32_e32 v27, v27
	v_add_f32_e32 v4, 1.0, v4
	v_add_f32_e32 v19, 1.0, v19
	v_add_f32_e32 v26, 1.0, v26
	v_add_f32_e32 v27, 1.0, v27
	v_rcp_f32_e32 v33, v4
	v_rcp_f32_e32 v35, v19
	v_rcp_f32_e32 v37, v26
	v_rcp_f32_e32 v39, v27
	v_lshlrev_b32_e32 v20, 16, v22
	v_and_b32_e32 v22, 0xffff0000, v22
	v_mov_b32_e32 v32, v5
	v_pk_mul_f32 v[20:21], v[32:33], v[20:21]
	v_pk_mul_f32 v[22:23], v[34:35], v[22:23]
	v_pk_mul_f32 v[24:25], v[36:37], v[24:25]
	v_mov_b32_e32 v17, v3
	v_or_b32_e32 v16, 0x120, v2
	v_pk_mul_f32 v[26:27], v[38:39], v[30:31]
	v_lshl_add_u64 v[16:17], v[12:13], 0, v[16:17]
	s_waitcnt vmcnt(31)
	v_and_b32_e32 v31, 0xffff0000, v105
	s_waitcnt vmcnt(29)
	v_mul_f32_e32 v4, v116, v20
	v_mul_f32_e32 v8, v117, v22
	v_mul_f32_e32 v9, v118, v24
	v_mul_f32_e32 v10, v119, v26
	v_mul_f32_e32 v8, v8, v23
	v_mul_f32_e32 v9, v9, v25
	v_mul_f32_e32 v4, v4, v21
	v_mul_f32_e32 v10, v10, v27
	v_cvt_pk_bf16_f32 v8, v4, v8
	v_cvt_pk_bf16_f32 v9, v9, v10
	global_store_dwordx2 v[16:17], v[8:9], off
	ds_read2_b64 v[20:23], v109 offset0:40 offset1:44
	v_lshlrev_b32_e32 v25, 16, v104
	v_lshlrev_b32_e32 v27, 16, v105
	v_mul_f32_e32 v4, 0xbfb8aa3b, v25
	v_mul_f32_e32 v29, 0xbfb8aa3b, v31
	s_waitcnt lgkmcnt(0)
	v_lshlrev_b32_e32 v26, 16, v21
	v_and_b32_e32 v30, 0xffff0000, v21
	v_and_b32_e32 v21, 0xffff0000, v104
	v_mul_f32_e32 v19, 0xbfb8aa3b, v21
	v_mul_f32_e32 v28, 0xbfb8aa3b, v27
	v_exp_f32_e32 v4, v4
	v_exp_f32_e32 v19, v19
	v_exp_f32_e32 v28, v28
	v_exp_f32_e32 v29, v29
	v_add_f32_e32 v4, 1.0, v4
	v_add_f32_e32 v19, 1.0, v19
	v_add_f32_e32 v28, 1.0, v28
	v_add_f32_e32 v29, 1.0, v29
	v_rcp_f32_e32 v33, v4
	v_rcp_f32_e32 v35, v19
	v_rcp_f32_e32 v37, v28
	v_rcp_f32_e32 v39, v29
	v_lshlrev_b32_e32 v24, 16, v20
	v_and_b32_e32 v20, 0xffff0000, v20
	v_pk_mul_f32 v[24:25], v[32:33], v[24:25]
	v_pk_mul_f32 v[20:21], v[34:35], v[20:21]
	v_pk_mul_f32 v[26:27], v[36:37], v[26:27]
	v_mov_b32_e32 v17, v3
	v_or_b32_e32 v16, 0x140, v2
	v_pk_mul_f32 v[28:29], v[38:39], v[30:31]
	v_lshl_add_u64 v[16:17], v[12:13], 0, v[16:17]
	v_mov_b32_e32 v30, v5
	s_waitcnt vmcnt(29)
	v_mul_f32_e32 v4, v120, v24
	v_mul_f32_e32 v8, v121, v20
	v_mul_f32_e32 v9, v122, v26
	v_mul_f32_e32 v10, v123, v28
	v_mul_f32_e32 v8, v8, v21
	v_mul_f32_e32 v9, v9, v27
	v_mul_f32_e32 v4, v4, v25
	v_mul_f32_e32 v10, v10, v29
	v_cvt_pk_bf16_f32 v8, v4, v8
	v_cvt_pk_bf16_f32 v9, v9, v10
	global_store_dwordx2 v[16:17], v[8:9], off
	v_lshlrev_b32_e32 v26, 16, v23
	v_and_b32_e32 v28, 0xffff0000, v23
	v_lshlrev_b32_e32 v21, 16, v106
	v_and_b32_e32 v23, 0xffff0000, v106
	v_lshlrev_b32_e32 v27, 16, v107
	v_and_b32_e32 v29, 0xffff0000, v107
	v_mul_f32_e32 v4, 0xbfb8aa3b, v21
	v_mul_f32_e32 v6, 0xbfb8aa3b, v23
	v_mul_f32_e32 v7, 0xbfb8aa3b, v27
	v_mul_f32_e32 v19, 0xbfb8aa3b, v29
	v_exp_f32_e32 v4, v4
	v_exp_f32_e32 v6, v6
	v_exp_f32_e32 v7, v7
	v_exp_f32_e32 v19, v19
	v_add_f32_e32 v4, 1.0, v4
	v_add_f32_e32 v6, 1.0, v6
	v_add_f32_e32 v7, 1.0, v7
	v_add_f32_e32 v19, 1.0, v19
	v_rcp_f32_e32 v31, v4
	v_rcp_f32_e32 v33, v6
	v_rcp_f32_e32 v35, v7
	v_rcp_f32_e32 v37, v19
	v_lshlrev_b32_e32 v20, 16, v22
	v_and_b32_e32 v22, 0xffff0000, v22
	v_pk_mul_f32 v[6:7], v[30:31], v[20:21]
	v_pk_mul_f32 v[20:21], v[32:33], v[22:23]
	v_pk_mul_f32 v[22:23], v[34:35], v[26:27]
	v_mov_b32_e32 v17, v3
	v_or_b32_e32 v16, 0x160, v2
	v_pk_mul_f32 v[26:27], v[36:37], v[28:29]
	v_lshl_add_u64 v[16:17], v[12:13], 0, v[16:17]
	s_waitcnt vmcnt(29)
	v_mul_f32_e32 v4, v124, v6
	v_mul_f32_e32 v6, v125, v20
	v_mul_f32_e32 v8, v126, v22
	v_mul_f32_e32 v9, v127, v26
	v_mul_f32_e32 v4, v4, v7
	v_mul_f32_e32 v6, v6, v21
	v_mul_f32_e32 v7, v8, v23
	v_mul_f32_e32 v8, v9, v27
	v_cvt_pk_bf16_f32 v6, v4, v6
	v_cvt_pk_bf16_f32 v7, v7, v8
	global_store_dwordx2 v[16:17], v[6:7], off
	ds_read2_b64 v[20:23], v109 offset0:48 offset1:52
	v_mov_b32_e32 v17, v3
	v_or_b32_e32 v16, 0x180, v2
	v_lshl_add_u64 v[14:15], v[12:13], 0, v[16:17]
	s_waitcnt lgkmcnt(0)
	v_lshlrev_b32_e32 v30, 16, v21
	v_and_b32_e32 v32, 0xffff0000, v21
	s_waitcnt vmcnt(29)
	v_lshlrev_b32_e32 v17, 16, v132
	v_and_b32_e32 v21, 0xffff0000, v132
	v_lshlrev_b32_e32 v31, 16, v133
	v_and_b32_e32 v33, 0xffff0000, v133
	v_mul_f32_e32 v4, 0xbfb8aa3b, v17
	v_mul_f32_e32 v19, 0xbfb8aa3b, v21
	v_mul_f32_e32 v24, 0xbfb8aa3b, v31
	v_mul_f32_e32 v25, 0xbfb8aa3b, v33
	v_exp_f32_e32 v4, v4
	v_exp_f32_e32 v19, v19
	v_exp_f32_e32 v24, v24
	v_exp_f32_e32 v25, v25
	v_add_f32_e32 v4, 1.0, v4
	v_add_f32_e32 v19, 1.0, v19
	v_add_f32_e32 v24, 1.0, v24
	v_add_f32_e32 v25, 1.0, v25
	v_rcp_f32_e32 v35, v4
	v_rcp_f32_e32 v37, v19
	v_rcp_f32_e32 v39, v24
	v_rcp_f32_e32 v41, v25
	v_lshlrev_b32_e32 v16, 16, v20
	v_and_b32_e32 v20, 0xffff0000, v20
	v_pk_mul_f32 v[16:17], v[34:35], v[16:17]
	v_pk_mul_f32 v[20:21], v[36:37], v[20:21]
	v_pk_mul_f32 v[24:25], v[38:39], v[30:31]
	v_pk_mul_f32 v[30:31], v[40:41], v[32:33]
	v_mov_b32_e32 v32, v5
	s_waitcnt vmcnt(28)
	v_mul_f32_e32 v4, v134, v16
	v_mul_f32_e32 v8, v135, v20
	v_mul_f32_e32 v9, v136, v24
	v_mul_f32_e32 v10, v137, v30
	v_mul_f32_e32 v8, v8, v21
	v_mul_f32_e32 v9, v9, v25
	v_mul_f32_e32 v4, v4, v17
	v_mul_f32_e32 v10, v10, v31
	v_cvt_pk_bf16_f32 v8, v4, v8
	v_cvt_pk_bf16_f32 v9, v9, v10
	global_store_dwordx2 v[14:15], v[8:9], off
	v_lshlrev_b32_e32 v16, 16, v22
	v_and_b32_e32 v20, 0xffff0000, v22
	v_lshlrev_b32_e32 v22, 16, v23
	v_and_b32_e32 v24, 0xffff0000, v23
	s_waitcnt vmcnt(28)
	v_lshlrev_b32_e32 v17, 16, v138
	v_and_b32_e32 v21, 0xffff0000, v138
	v_lshlrev_b32_e32 v23, 16, v139
	v_and_b32_e32 v25, 0xffff0000, v139
	v_mul_f32_e32 v4, 0xbfb8aa3b, v17
	v_mul_f32_e32 v19, 0xbfb8aa3b, v21
	v_mul_f32_e32 v26, 0xbfb8aa3b, v23
	v_mul_f32_e32 v27, 0xbfb8aa3b, v25
	v_exp_f32_e32 v4, v4
	v_exp_f32_e32 v19, v19
	v_exp_f32_e32 v26, v26
	v_exp_f32_e32 v27, v27
	v_add_f32_e32 v4, 1.0, v4
	v_add_f32_e32 v19, 1.0, v19
	v_add_f32_e32 v26, 1.0, v26
	v_add_f32_e32 v27, 1.0, v27
	v_rcp_f32_e32 v31, v4
	v_rcp_f32_e32 v33, v19
	v_rcp_f32_e32 v35, v26
	v_rcp_f32_e32 v37, v27
	v_mov_b32_e32 v30, v5
	v_pk_mul_f32 v[16:17], v[30:31], v[16:17]
	v_pk_mul_f32 v[20:21], v[32:33], v[20:21]
	v_pk_mul_f32 v[22:23], v[34:35], v[22:23]
	v_mov_b32_e32 v15, v3
	v_or_b32_e32 v14, 0x1a0, v2
	v_pk_mul_f32 v[24:25], v[36:37], v[24:25]
	v_lshl_add_u64 v[14:15], v[12:13], 0, v[14:15]
	s_waitcnt vmcnt(27)
	v_and_b32_e32 v27, 0xffff0000, v141
	s_waitcnt vmcnt(25)
	v_mul_f32_e32 v4, v144, v16
	v_mul_f32_e32 v8, v145, v20
	v_mul_f32_e32 v9, v146, v22
	v_mul_f32_e32 v10, v147, v24
	v_mul_f32_e32 v8, v8, v21
	v_mul_f32_e32 v9, v9, v23
	v_mul_f32_e32 v4, v4, v17
	v_mul_f32_e32 v10, v10, v25
	v_cvt_pk_bf16_f32 v8, v4, v8
	v_cvt_pk_bf16_f32 v9, v9, v10
	global_store_dwordx2 v[14:15], v[8:9], off
	ds_read2_b64 v[14:17], v109 offset0:56 offset1:60
	v_lshlrev_b32_e32 v23, 16, v140
	v_lshlrev_b32_e32 v25, 16, v141
	v_mul_f32_e32 v4, 0xbfb8aa3b, v23
	v_mul_f32_e32 v29, 0xbfb8aa3b, v27
	s_waitcnt lgkmcnt(0)
	v_lshlrev_b32_e32 v24, 16, v15
	v_and_b32_e32 v26, 0xffff0000, v15
	v_and_b32_e32 v15, 0xffff0000, v140
	v_mul_f32_e32 v19, 0xbfb8aa3b, v15
	v_mul_f32_e32 v28, 0xbfb8aa3b, v25
	v_exp_f32_e32 v4, v4
	v_exp_f32_e32 v19, v19
	v_exp_f32_e32 v28, v28
	v_exp_f32_e32 v29, v29
	v_add_f32_e32 v4, 1.0, v4
	v_add_f32_e32 v19, 1.0, v19
	v_add_f32_e32 v28, 1.0, v28
	v_add_f32_e32 v29, 1.0, v29
	v_rcp_f32_e32 v31, v4
	v_rcp_f32_e32 v33, v19
	v_rcp_f32_e32 v35, v28
	v_rcp_f32_e32 v37, v29
	v_lshlrev_b32_e32 v22, 16, v14
	v_and_b32_e32 v14, 0xffff0000, v14
	v_pk_mul_f32 v[22:23], v[30:31], v[22:23]
	v_pk_mul_f32 v[14:15], v[32:33], v[14:15]
	v_pk_mul_f32 v[24:25], v[34:35], v[24:25]
	v_mov_b32_e32 v21, v3
	v_or_b32_e32 v20, 0x1c0, v2
	v_pk_mul_f32 v[26:27], v[36:37], v[26:27]
	v_lshl_add_u64 v[20:21], v[12:13], 0, v[20:21]
	v_or_b32_e32 v2, 0x1e0, v2
	v_mov_b32_e32 v28, v5
	v_lshlrev_b32_e32 v19, 16, v143
	v_lshl_add_u64 v[12:13], v[12:13], 0, v[2:3]
	v_mov_b32_e32 v30, v0
	s_waitcnt vmcnt(25)
	v_mul_f32_e32 v4, v148, v22
	v_mul_f32_e32 v8, v149, v14
	v_mul_f32_e32 v9, v150, v24
	v_mul_f32_e32 v10, v151, v26
	v_mul_f32_e32 v8, v8, v15
	v_mul_f32_e32 v9, v9, v25
	v_mul_f32_e32 v4, v4, v23
	v_mul_f32_e32 v10, v10, v27
	v_cvt_pk_bf16_f32 v8, v4, v8
	v_cvt_pk_bf16_f32 v9, v9, v10
	global_store_dwordx2 v[20:21], v[8:9], off
	v_lshlrev_b32_e32 v18, 16, v17
	v_and_b32_e32 v20, 0xffff0000, v17
	v_mov_b32_e32 v22, v5
	v_mov_b32_e32 v24, v5
	v_mov_b32_e32 v26, v5
	v_lshlrev_b32_e32 v5, 16, v142
	v_and_b32_e32 v17, 0xffff0000, v142
	v_and_b32_e32 v21, 0xffff0000, v143
	v_mul_f32_e32 v2, 0xbfb8aa3b, v5
	v_mul_f32_e32 v6, 0xbfb8aa3b, v17
	v_mul_f32_e32 v7, 0xbfb8aa3b, v19
	v_mul_f32_e32 v23, 0xbfb8aa3b, v21
	v_exp_f32_e32 v2, v2
	v_exp_f32_e32 v6, v6
	v_exp_f32_e32 v7, v7
	v_exp_f32_e32 v23, v23
	v_add_f32_e32 v2, 1.0, v2
	v_add_f32_e32 v6, 1.0, v6
	v_add_f32_e32 v7, 1.0, v7
	v_add_f32_e32 v29, 1.0, v23
	v_rcp_f32_e32 v23, v2
	v_rcp_f32_e32 v25, v6
	v_rcp_f32_e32 v27, v7
	v_rcp_f32_e32 v29, v29
	v_lshlrev_b32_e32 v4, 16, v16
	v_and_b32_e32 v16, 0xffff0000, v16
	v_pk_mul_f32 v[4:5], v[22:23], v[4:5]
	v_pk_mul_f32 v[6:7], v[24:25], v[16:17]
	v_pk_mul_f32 v[16:17], v[26:27], v[18:19]
	v_pk_mul_f32 v[18:19], v[28:29], v[20:21]
	v_mov_b64_e32 v[14:15], s[88:89]
	s_waitcnt vmcnt(25)
	v_mul_f32_e32 v2, v152, v4
	v_mul_f32_e32 v4, v153, v6
	v_mul_f32_e32 v6, v154, v16
	v_mul_f32_e32 v8, v155, v18
	v_mul_f32_e32 v2, v2, v5
	v_mul_f32_e32 v4, v4, v7
	v_mul_f32_e32 v5, v6, v17
	v_mul_f32_e32 v6, v8, v19
	v_cvt_pk_bf16_f32 v4, v2, v4
	v_cvt_pk_bf16_f32 v5, v5, v6
	global_store_dwordx2 v[12:13], v[4:5], off
	s_nop 0
	v_and_b32_e32 v52, 15, v30
	v_ashrrev_i32_e32 v2, 6, v30
	v_or_b32_e32 v5, s20, v52
	v_ashrrev_i32_e32 v46, 1, v30
	v_lshl_add_u32 v116, v2, 4, v5
	v_lshl_add_u32 v4, s0, 8, v46
	v_mad_i64_i32 v[118:119], s[0:1], v116, s92, v[14:15]
	v_ashrrev_i32_e32 v5, 31, v4
	v_readlane_b32 s0, v244, 50
	v_and_b32_e32 v50, 1, v30
	v_lshlrev_b64 v[4:5], 10, v[4:5]
	v_readlane_b32 s1, v244, 51
	v_bfe_u32 v47, v30, 4, 2
	v_lshlrev_b32_e32 v44, 6, v50
	v_lshl_add_u64 v[4:5], s[0:1], 0, v[4:5]
	v_lshlrev_b32_e32 v114, 4, v47
	v_lshl_add_u64 v[20:21], v[4:5], 0, v[44:45]
	v_lshl_add_u64 v[120:121], v[118:119], 0, v[114:115]
	s_waitcnt vmcnt(16)
	v_mov_b64_e32 v[4:5], v[156:157]
	v_mov_b64_e32 v[6:7], v[158:159]
	v_mov_b64_e32 v[12:13], v[160:161]
	v_mov_b64_e32 v[14:15], v[162:163]
	v_mov_b64_e32 v[16:17], v[164:165]
	v_mov_b64_e32 v[18:19], v[166:167]
	v_mov_b64_e32 v[8:9], v[172:173]
	v_mov_b64_e32 v[10:11], v[174:175]
	v_mov_b64_e32 v[28:29], v[176:177]
	v_mov_b64_e32 v[30:31], v[178:179]
	v_mov_b64_e32 v[32:33], v[196:197]
	v_mov_b64_e32 v[34:35], v[198:199]
	v_mov_b64_e32 v[36:37], v[200:201]
	v_mov_b64_e32 v[38:39], v[202:203]
	v_mov_b64_e32 v[40:41], v[204:205]
	v_mov_b64_e32 v[42:43], v[206:207]
	s_nop 0
	v_mov_b64_e32 v[20:21], v[208:209]
	v_mov_b64_e32 v[22:23], v[210:211]
	v_mov_b64_e32 v[24:25], v[212:213]
	v_mov_b64_e32 v[26:27], v[214:215]
	v_readlane_b32 s0, v243, 0
	v_mul_lo_u32 v45, v46, s97
	s_and_b32 s0, s0, 7
	v_add_u32_e32 v48, 0, v45
	s_lshl_b32 s2, s0, 18
	v_add_u32_e32 v132, v48, v44
	v_mad_u64_u32 v[48:49], s[0:1], v46, s98, v[48:49]
	v_mul_u32_u24_e32 v45, 0x4200, v50
	v_lshlrev_b32_e32 v50, 7, v50
	v_mul_lo_u32 v131, v2, s93
	v_lshlrev_b32_e32 v2, 3, v47
	v_lshl_add_u64 v[122:123], s[10:11], 0, v[50:51]
	v_lshlrev_b32_e32 v50, 5, v47
	v_or_b32_e32 v47, 16, v52
	s_movk_i32 s0, 0x210
	v_lshl_add_u64 v[124:125], s[8:9], 0, v[50:51]
	global_load_dwordx4 v[224:227], v[124:125], off
	global_load_dwordx4 v[228:231], v[124:125], off offset:128
	global_load_dwordx4 v[232:235], v[124:125], off offset:16
	global_load_dwordx4 v[236:239], v[124:125], off offset:144
	v_mul_u32_u24_e32 v51, 0x210, v47
	v_mad_u32_u24 v47, v52, s0, v131
	v_add3_u32 v134, v47, v2, s96
	v_ashrrev_i32_e32 v47, 31, v46
	v_lshlrev_b64 v[46:47], 10, v[46:47]
	v_add_u32_e32 v49, 0, v114
	s_mov_b32 s1, s3
	v_lshl_add_u64 v[46:47], s[2:3], 0, v[46:47]
	v_mov_b32_e32 v133, v49
	v_mul_u32_u24_e32 v50, 0x90, v52
	v_writelane_b32 v244, s0, 62
	v_or_b32_e32 v46, v46, v44
	v_mul_u32_u24_e32 v115, 0x210, v52
	v_ashrrev_i32_e32 v117, 31, v116
	v_writelane_b32 v244, s1, 63
	v_lshl_add_u64 v[126:127], s[6:7], 0, v[46:47]
	s_mov_b64 s[0:1], 64
	v_and_b32_e32 v241, 24, v48
	v_and_b32_e32 v242, 32, v48
	v_and_b32_e32 v48, 0xffffffc7, v48
	v_lshlrev_b32_e32 v241, 1, v241
	v_lshrrev_b32_e32 v242, 2, v242
	v_or3_b32 v48, v48, v241, v242
	v_add_u32_e32 v135, v48, v45
	v_add_u32_e32 v136, v49, v50
	v_add_u32_e32 v137, v133, v51
	v_add_u32_e32 v240, v133, v115
	v_add_u32_e32 v240, 0x9000, v240
	v_add_u32_e32 v241, 0x9000, v137
	v_add_u32_e32 v242, 0xb000, v137
	v_add_u32_e32 v245, 0xd000, v137
	v_bfe_u32 v129, v0, 4, 2
	v_mul_u32_u24_e32 v171, 0x1200, v116
	v_lshl_add_u32 v129, v129, 3, v171
	v_add_u32_e32 v129, 0x1000, v129
	global_load_dwordx2 v[150:151], v129, s[88:89]
	global_load_dwordx2 v[152:153], v129, s[88:89] offset:32
	global_load_dwordx2 v[154:155], v129, s[88:89] offset:64
	global_load_dwordx2 v[156:157], v129, s[88:89] offset:96
	global_load_dwordx2 v[158:159], v129, s[88:89] offset:128
	global_load_dwordx2 v[160:161], v129, s[88:89] offset:160
	global_load_dwordx2 v[162:163], v129, s[88:89] offset:192
	global_load_dwordx2 v[164:165], v129, s[88:89] offset:224
	global_load_dwordx2 v[166:167], v129, s[88:89] offset:256
	global_load_dwordx2 v[168:169], v129, s[88:89] offset:288
	global_load_dwordx2 v[248:249], v129, s[88:89] offset:320
	global_load_dwordx2 v[250:251], v129, s[88:89] offset:352
	global_load_dwordx2 v[252:253], v129, s[88:89] offset:384
	global_load_dwordx2 v[254:255], v129, s[88:89] offset:416
	s_branch .LBB0_210

.LBB0_215:
	s_waitcnt vmcnt(0)
	s_mov_b64 s[0:1], 0x1000
	v_lshl_add_u64 v[16:17], v[118:119], 0, s[0:1]
	v_lshl_add_u64 v[4:5], v[16:17], 0, v[2:3]
	v_mov_b64_e32 v[50:51], v[4:5]
	v_mov_b64_e32 v[8:9], v[150:151]
	v_readlane_b32 s4, v244, 0
	v_readlane_b32 s8, v244, 4
	v_readlane_b32 s9, v244, 5
	v_mov_b32_e32 v14, v130
	s_nop 1
	v_permlane16_swap_b32 v14, v130
	v_readlane_b32 s5, v244, 1
	v_readlane_b32 s6, v244, 2
	v_readlane_b32 s7, v244, 3
	v_readlane_b32 s4, v244, 57
	global_load_dwordx4 v[4:7], v114, s[8:9] offset:3072
	v_mov_b64_e32 v[52:53], v[152:153]
	v_mov_b64_e32 v[54:55], v[154:155]
	v_mov_b64_e32 v[56:57], v[156:157]
	global_load_dwordx4 v[58:61], v114, s[8:9] offset:3136
	global_load_dwordx4 v[62:65], v114, s[8:9] offset:3200
	global_load_dwordx4 v[66:69], v114, s[8:9] offset:3264
	v_mov_b64_e32 v[70:71], v[158:159]
	global_load_dwordx4 v[72:75], v114, s[8:9] offset:3328
	v_mov_b64_e32 v[76:77], v[160:161]
	v_mov_b64_e32 v[78:79], v[162:163]
	v_mov_b64_e32 v[80:81], v[164:165]
	global_load_dwordx4 v[82:85], v114, s[8:9] offset:3392
	global_load_dwordx4 v[86:89], v114, s[8:9] offset:3456
	global_load_dwordx4 v[90:93], v114, s[8:9] offset:3520
	v_mov_b64_e32 v[94:95], v[166:167]
	global_load_dwordx4 v[96:99], v114, s[8:9] offset:3584
	v_mov_b64_e32 v[100:101], v[168:169]
	v_mov_b64_e32 v[102:103], v[248:249]
	v_mov_b64_e32 v[104:105], v[250:251]
	global_load_dwordx4 v[106:109], v114, s[8:9] offset:3648
	global_load_dwordx4 v[120:123], v114, s[8:9] offset:3712
	global_load_dwordx4 v[124:127], v114, s[8:9] offset:3776
	v_mov_b64_e32 v[110:111], v[252:253]
	global_load_dwordx4 v[132:135], v114, s[8:9] offset:3840
	v_mov_b64_e32 v[136:137], v[254:255]
	global_load_dwordx2 v[138:139], v[50:51], off offset:448
	global_load_dwordx2 v[140:141], v[50:51], off offset:480
	global_load_dwordx4 v[142:145], v114, s[8:9] offset:3904
	global_load_dwordx4 v[146:149], v114, s[8:9] offset:3968
	global_load_dwordx4 v[150:153], v114, s[8:9] offset:4032
	v_readlane_b32 s24, v244, 16
	v_readlane_b32 s25, v244, 17
	v_readlane_b32 s26, v244, 42
	v_readlane_b32 s27, v244, 43
	v_readlane_b32 s28, v244, 44
	v_readlane_b32 s29, v244, 45
	v_readlane_b32 s30, v244, 10
	v_readlane_b32 s31, v244, 11
	v_readlane_b32 s32, v244, 14
	v_readlane_b32 s33, v244, 15
	v_readlane_b32 s34, v244, 48
	v_readlane_b32 s35, v244, 49
	v_lshlrev_b32_e32 v113, 2, v0
	v_and_b32_e32 v129, 63, v0
	v_lshrrev_b32_e32 v179, 6, v0
	v_lshlrev_b32_e32 v129, 4, v129
	v_add_u32_e32 v128, 0x1000, v113
	v_lshl_add_u32 v129, v179, 13, v129
	s_add_u32 s36, s34, 0x10000
	s_addc_u32 s37, s35, 0
	v_add_u32_e32 v179, 0x1000, v129
	global_load_dword v154, v113, s[24:25]
	global_load_dword v155, v113, s[26:27]
	global_load_dword v168, v113, s[26:27] offset:2048
	global_load_dword v169, v128, s[26:27]
	global_load_dword v171, v128, s[26:27] offset:2048
	global_load_dword v240, v113, s[28:29]
	global_load_dword v241, v113, s[30:31]
	global_load_dword v242, v113, s[32:33]
	global_load_dwordx4 v[156:159], v129, s[34:35]
	global_load_dwordx4 v[160:163], v129, s[34:35] offset:1024
	global_load_dwordx4 v[164:167], v129, s[34:35] offset:2048
	global_load_dwordx4 v[172:175], v129, s[34:35] offset:3072
	global_load_dwordx4 v[196:199], v129, s[36:37]
	global_load_dwordx4 v[200:203], v129, s[36:37] offset:1024
	global_load_dwordx4 v[204:207], v129, s[36:37] offset:2048
	global_load_dwordx4 v[208:211], v129, s[36:37] offset:3072
	global_load_dwordx4 v[212:215], v179, s[34:35]
	global_load_dwordx4 v[216:219], v179, s[36:37]
	global_load_dwordx4 v[220:223], v179, s[34:35] offset:1024
	global_load_dwordx4 v[224:227], v179, s[36:37] offset:1024
	global_load_dwordx4 v[228:231], v179, s[34:35] offset:2048
	global_load_dwordx4 v[232:235], v179, s[36:37] offset:2048
	global_load_dwordx4 v[236:239], v179, s[34:35] offset:3072
	global_load_dwordx4 v[248:251], v179, s[36:37] offset:3072
	s_waitcnt lgkmcnt(0)
	v_add_f32_e32 v14, v130, v14
	v_mov_b32_e32 v15, v14
	s_nop 1
	v_permlane32_swap_b32 v15, v14
	v_lshlrev_b64 v[10:11], 11, v[116:117]
	v_readlane_b32 s6, v244, 59
	v_readlane_b32 s7, v244, 60
	v_add_u32_e32 v12, s96, v131
	s_mov_b64 s[0:1], 0xdde0600
	v_or_b32_e32 v22, 32, v2
	v_mov_b32_e32 v23, v3
	v_or_b32_e32 v24, 64, v2
	v_mov_b32_e32 v25, v3
	v_or_b32_e32 v18, 0x60, v2
	v_mov_b32_e32 v19, v3
	v_lshl_add_u64 v[10:11], s[6:7], 0, v[10:11]
	s_waitcnt lgkmcnt(0)
	v_add_f32_e32 v14, v14, v15
	v_add3_u32 v26, v12, v115, v2
	v_lshl_add_u64 v[12:13], v[10:11], 0, s[0:1]
	v_lshl_add_u64 v[10:11], v[16:17], 0, v[22:23]
	v_lshl_add_u64 v[20:21], v[16:17], 0, v[24:25]
	v_lshl_add_u64 v[32:33], v[16:17], 0, v[18:19]
	v_fmamk_f32 v14, v14, 0x3b800000, v180
	s_mov_b32 s0, 0x800000
	ds_read2_b64 v[28:31], v26 offset1:4
	s_nop 0
	s_nop 0
	v_mul_f32_e32 v15, 0x4b800000, v14
	v_cmp_gt_f32_e32 vcc, s0, v14
	v_lshl_add_u64 v[34:35], v[12:13], 0, v[2:3]
	s_waitcnt lgkmcnt(0)
	v_lshlrev_b32_e32 v33, 16, v28
	v_cndmask_b32_e32 v14, v14, v15, vcc
	v_rsq_f32_e32 v14, v14
	v_and_b32_e32 v39, 0xffff0000, v28
	v_lshlrev_b32_e32 v41, 16, v29
	v_and_b32_e32 v29, 0xffff0000, v29
	v_mul_f32_e32 v15, 0x45800000, v14
	v_cndmask_b32_e32 v15, v14, v15, vcc
	v_lshl_add_u64 v[18:19], v[12:13], 0, v[18:19]
	v_mov_b32_e32 v44, v15
	v_mov_b32_e32 v46, v15
	v_mov_b32_e32 v48, v15
	v_readlane_b32 s36, v244, 10
	v_readlane_b32 s42, v244, 16
	v_readlane_b32 s43, v244, 17
	v_readlane_b32 s10, v244, 6
	v_readlane_b32 s11, v244, 7
	v_readlane_b32 s5, v244, 58
	s_movk_i32 s0, 0x1000
	v_readlane_b32 s37, v244, 11
	v_readlane_b32 s40, v244, 14
	v_readlane_b32 s41, v244, 15
	s_mov_b32 s3, 0x7f800000
	s_mov_b32 s2, 0x33800000
	v_readlane_b32 s38, v244, 12
	v_readlane_b32 s39, v244, 13
	v_readlane_b32 s44, v244, 18
	v_readlane_b32 s45, v244, 19
	v_readlane_b32 s46, v244, 20
	v_readlane_b32 s47, v244, 21
	v_readlane_b32 s48, v244, 22
	v_readlane_b32 s49, v244, 23
	v_readlane_b32 s50, v244, 24
	v_readlane_b32 s51, v244, 25
	v_lshlrev_b32_e32 v32, 16, v8
	v_and_b32_e32 v38, 0xffff0000, v8
	v_mul_f32_e32 v8, 0xbfb8aa3b, v32
	v_exp_f32_e32 v8, v8
	v_lshlrev_b32_e32 v40, 16, v9
	v_and_b32_e32 v28, 0xffff0000, v9
	v_mul_f32_e32 v9, 0xbfb8aa3b, v38
	v_exp_f32_e32 v9, v9
	v_add_f32_e32 v8, 1.0, v8
	v_rcp_f32_e32 v14, v8
	v_mul_f32_e32 v27, 0xbfb8aa3b, v40
	v_exp_f32_e32 v27, v27
	v_add_f32_e32 v43, 1.0, v9
	v_pk_mul_f32 v[8:9], v[14:15], v[32:33]
	v_rcp_f32_e32 v14, v43
	v_mul_f32_e32 v42, 0xbfb8aa3b, v28
	v_exp_f32_e32 v42, v42
	v_add_f32_e32 v27, 1.0, v27
	v_pk_mul_f32 v[32:33], v[14:15], v[38:39]
	v_rcp_f32_e32 v14, v27
	s_waitcnt vmcnt(41)
	v_mul_f32_e32 v4, v4, v9
	v_add_f32_e32 v42, 1.0, v42
	v_mul_f32_e32 v8, v8, v4
	v_mul_f32_e32 v4, v5, v33
	v_mul_f32_e32 v9, v32, v4
	v_pk_mul_f32 v[4:5], v[14:15], v[40:41]
	v_rcp_f32_e32 v14, v42
	v_mul_f32_e32 v5, v6, v5
	v_mul_f32_e32 v6, v4, v5
	v_cvt_pk_bf16_f32 v8, v8, v9
	v_pk_mul_f32 v[4:5], v[14:15], v[28:29]
	v_and_b32_e32 v29, 0xffff0000, v52
	v_mul_f32_e32 v5, v7, v5
	v_mul_f32_e32 v4, v4, v5
	v_cvt_pk_bf16_f32 v9, v6, v4
	global_store_dwordx2 v[34:35], v[8:9], off
	v_lshl_add_u64 v[8:9], v[12:13], 0, v[22:23]
	v_lshlrev_b32_e32 v23, 16, v52
	v_lshlrev_b32_e32 v22, 16, v30
	v_and_b32_e32 v28, 0xffff0000, v30
	v_lshlrev_b32_e32 v30, 16, v31
	v_and_b32_e32 v32, 0xffff0000, v31
	v_lshlrev_b32_e32 v31, 16, v53
	v_and_b32_e32 v33, 0xffff0000, v53
	v_mul_f32_e32 v10, 0xbfb8aa3b, v23
	v_mul_f32_e32 v11, 0xbfb8aa3b, v29
	v_mul_f32_e32 v14, 0xbfb8aa3b, v31
	v_mul_f32_e32 v27, 0xbfb8aa3b, v33
	v_exp_f32_e32 v10, v10
	v_exp_f32_e32 v11, v11
	v_exp_f32_e32 v14, v14
	v_exp_f32_e32 v27, v27
	v_add_f32_e32 v10, 1.0, v10
	v_add_f32_e32 v11, 1.0, v11
	v_add_f32_e32 v14, 1.0, v14
	v_add_f32_e32 v27, 1.0, v27
	v_rcp_f32_e32 v35, v10
	v_rcp_f32_e32 v39, v11
	v_rcp_f32_e32 v41, v14
	v_rcp_f32_e32 v43, v27
	v_mov_b32_e32 v34, v15
	v_mov_b32_e32 v38, v15
	v_mov_b32_e32 v40, v15
	v_mov_b32_e32 v42, v15
	v_pk_mul_f32 v[10:11], v[34:35], v[22:23]
	v_pk_mul_f32 v[22:23], v[38:39], v[28:29]
	v_pk_mul_f32 v[28:29], v[40:41], v[30:31]
	v_pk_mul_f32 v[30:31], v[42:43], v[32:33]
	v_mov_b32_e32 v32, v15
	s_waitcnt vmcnt(41)
	v_mul_f32_e32 v4, v58, v10
	v_mul_f32_e32 v5, v59, v22
	v_mul_f32_e32 v6, v60, v28
	v_mul_f32_e32 v7, v61, v30
	v_mul_f32_e32 v4, v4, v11
	v_mul_f32_e32 v5, v5, v23
	v_mul_f32_e32 v6, v6, v29
	v_mul_f32_e32 v7, v7, v31
	v_cvt_pk_bf16_f32 v4, v4, v5
	v_cvt_pk_bf16_f32 v5, v6, v7
	global_store_dwordx2 v[8:9], v[4:5], off
	ds_read2_b64 v[4:7], v26 offset0:8 offset1:12
	v_lshlrev_b32_e32 v29, 16, v55
	v_lshl_add_u64 v[22:23], v[12:13], 0, v[24:25]
	v_lshlrev_b32_e32 v25, 16, v54
	v_and_b32_e32 v31, 0xffff0000, v55
	s_waitcnt lgkmcnt(0)
	v_lshlrev_b32_e32 v28, 16, v5
	v_and_b32_e32 v30, 0xffff0000, v5
	v_and_b32_e32 v5, 0xffff0000, v54
	v_mul_f32_e32 v27, 0xbfb8aa3b, v5
	v_mul_f32_e32 v33, 0xbfb8aa3b, v29
	v_mul_f32_e32 v14, 0xbfb8aa3b, v25
	v_mul_f32_e32 v35, 0xbfb8aa3b, v31
	v_exp_f32_e32 v27, v27
	v_exp_f32_e32 v33, v33
	v_exp_f32_e32 v14, v14
	v_exp_f32_e32 v35, v35
	v_add_f32_e32 v27, 1.0, v27
	v_add_f32_e32 v36, 1.0, v33
	v_add_f32_e32 v14, 1.0, v14
	v_add_f32_e32 v37, 1.0, v35
	v_rcp_f32_e32 v35, v27
	v_rcp_f32_e32 v39, v36
	v_rcp_f32_e32 v33, v14
	v_rcp_f32_e32 v41, v37
	v_lshlrev_b32_e32 v24, 16, v4
	v_and_b32_e32 v4, 0xffff0000, v4
	v_pk_mul_f32 v[4:5], v[34:35], v[4:5]
	v_pk_mul_f32 v[28:29], v[38:39], v[28:29]
	v_pk_mul_f32 v[24:25], v[32:33], v[24:25]
	v_pk_mul_f32 v[30:31], v[40:41], v[30:31]
	v_mov_b32_e32 v36, v15
	s_waitcnt vmcnt(41)
	v_mul_f32_e32 v4, v63, v4
	v_mul_f32_e32 v9, v64, v28
	v_mul_f32_e32 v8, v62, v24
	v_mul_f32_e32 v10, v65, v30
	v_mul_f32_e32 v4, v4, v5
	v_mul_f32_e32 v5, v9, v29
	v_mul_f32_e32 v8, v8, v25
	v_mul_f32_e32 v9, v10, v31
	v_cvt_pk_bf16_f32 v4, v8, v4
	v_cvt_pk_bf16_f32 v5, v5, v9
	global_store_dwordx2 v[22:23], v[4:5], off
	v_or_b32_e32 v10, 0x80, v2
	v_mov_b32_e32 v11, v3
	v_lshl_add_u64 v[4:5], v[16:17], 0, v[10:11]
	v_lshlrev_b32_e32 v28, 16, v7
	v_and_b32_e32 v30, 0xffff0000, v7
	v_lshlrev_b32_e32 v5, 16, v56
	v_and_b32_e32 v7, 0xffff0000, v56
	v_lshlrev_b32_e32 v29, 16, v57
	v_and_b32_e32 v31, 0xffff0000, v57
	v_mul_f32_e32 v14, 0xbfb8aa3b, v5
	v_mul_f32_e32 v20, 0xbfb8aa3b, v7
	v_mul_f32_e32 v21, 0xbfb8aa3b, v29
	v_mul_f32_e32 v27, 0xbfb8aa3b, v31
	v_exp_f32_e32 v14, v14
	v_exp_f32_e32 v20, v20
	v_exp_f32_e32 v21, v21
	v_exp_f32_e32 v27, v27
	v_add_f32_e32 v14, 1.0, v14
	v_add_f32_e32 v20, 1.0, v20
	v_add_f32_e32 v21, 1.0, v21
	v_add_f32_e32 v27, 1.0, v27
	v_rcp_f32_e32 v33, v14
	v_rcp_f32_e32 v35, v20
	v_rcp_f32_e32 v37, v21
	v_rcp_f32_e32 v39, v27
	v_lshlrev_b32_e32 v4, 16, v6
	v_and_b32_e32 v6, 0xffff0000, v6
	v_pk_mul_f32 v[4:5], v[32:33], v[4:5]
	v_pk_mul_f32 v[6:7], v[34:35], v[6:7]
	v_pk_mul_f32 v[20:21], v[36:37], v[28:29]
	v_pk_mul_f32 v[28:29], v[38:39], v[30:31]
	v_lshl_add_u64 v[10:11], v[12:13], 0, v[10:11]
	s_waitcnt vmcnt(41)
	v_mul_f32_e32 v4, v66, v4
	v_mul_f32_e32 v6, v67, v6
	v_mul_f32_e32 v14, v68, v20
	v_mul_f32_e32 v20, v69, v28
	v_mul_f32_e32 v4, v4, v5
	v_mul_f32_e32 v5, v6, v7
	v_mul_f32_e32 v6, v14, v21
	v_mul_f32_e32 v7, v20, v29
	v_cvt_pk_bf16_f32 v4, v4, v5
	v_cvt_pk_bf16_f32 v5, v6, v7
	global_store_dwordx2 v[18:19], v[4:5], off
	ds_read2_b64 v[28:31], v26 offset0:16 offset1:20
	v_or_b32_e32 v22, 0xa0, v2
	v_mov_b32_e32 v23, v3
	v_or_b32_e32 v24, 0xc0, v2
	v_mov_b32_e32 v25, v3
	v_or_b32_e32 v18, 0xe0, v2
	v_mov_b32_e32 v19, v3
	v_lshl_add_u64 v[20:21], v[16:17], 0, v[22:23]
	v_lshl_add_u64 v[32:33], v[16:17], 0, v[24:25]
	v_lshl_add_u64 v[34:35], v[16:17], 0, v[18:19]
	s_nop 0
	s_nop 0
	s_waitcnt lgkmcnt(0)
	v_lshlrev_b32_e32 v38, 16, v29
	v_and_b32_e32 v40, 0xffff0000, v29
	v_lshlrev_b32_e32 v35, 16, v70
	v_and_b32_e32 v29, 0xffff0000, v70
	v_lshlrev_b32_e32 v39, 16, v71
	v_and_b32_e32 v41, 0xffff0000, v71
	v_mul_f32_e32 v8, 0xbfb8aa3b, v35
	v_mul_f32_e32 v9, 0xbfb8aa3b, v29
	v_mul_f32_e32 v14, 0xbfb8aa3b, v39
	v_mul_f32_e32 v27, 0xbfb8aa3b, v41
	v_exp_f32_e32 v8, v8
	v_exp_f32_e32 v9, v9
	v_exp_f32_e32 v14, v14
	v_exp_f32_e32 v27, v27
	v_add_f32_e32 v8, 1.0, v8
	v_add_f32_e32 v9, 1.0, v9
	v_add_f32_e32 v14, 1.0, v14
	v_add_f32_e32 v27, 1.0, v27
	v_rcp_f32_e32 v43, v8
	v_rcp_f32_e32 v45, v9
	v_rcp_f32_e32 v47, v14
	v_rcp_f32_e32 v49, v27
	v_lshlrev_b32_e32 v34, 16, v28
	v_and_b32_e32 v28, 0xffff0000, v28
	v_pk_mul_f32 v[8:9], v[42:43], v[34:35]
	v_pk_mul_f32 v[28:29], v[44:45], v[28:29]
	v_pk_mul_f32 v[34:35], v[46:47], v[38:39]
	v_pk_mul_f32 v[38:39], v[48:49], v[40:41]
	v_mov_b32_e32 v40, v15
	v_lshl_add_u64 v[18:19], v[12:13], 0, v[18:19]
	s_waitcnt vmcnt(41)
	v_mul_f32_e32 v4, v72, v8
	v_mul_f32_e32 v5, v73, v28
	v_mul_f32_e32 v6, v74, v34
	v_mul_f32_e32 v7, v75, v38
	v_mul_f32_e32 v4, v4, v9
	v_mul_f32_e32 v5, v5, v29
	v_mul_f32_e32 v6, v6, v35
	v_mul_f32_e32 v7, v7, v39
	v_cvt_pk_bf16_f32 v4, v4, v5
	v_cvt_pk_bf16_f32 v5, v6, v7
	global_store_dwordx2 v[10:11], v[4:5], off
	v_lshl_add_u64 v[8:9], v[12:13], 0, v[22:23]
	v_lshlrev_b32_e32 v11, 16, v76
	v_and_b32_e32 v23, 0xffff0000, v76
	v_lshlrev_b32_e32 v10, 16, v30
	v_and_b32_e32 v22, 0xffff0000, v30
	v_lshlrev_b32_e32 v28, 16, v31
	v_and_b32_e32 v30, 0xffff0000, v31
	v_lshlrev_b32_e32 v29, 16, v77
	v_and_b32_e32 v31, 0xffff0000, v77
	v_mul_f32_e32 v14, 0xbfb8aa3b, v11
	v_mul_f32_e32 v27, 0xbfb8aa3b, v23
	v_mul_f32_e32 v35, 0xbfb8aa3b, v29
	v_mul_f32_e32 v36, 0xbfb8aa3b, v31
	v_exp_f32_e32 v14, v14
	v_exp_f32_e32 v27, v27
	v_exp_f32_e32 v35, v35
	v_exp_f32_e32 v36, v36
	v_add_f32_e32 v14, 1.0, v14
	v_add_f32_e32 v27, 1.0, v27
	v_add_f32_e32 v37, 1.0, v35
	v_add_f32_e32 v36, 1.0, v36
	v_rcp_f32_e32 v35, v14
	v_rcp_f32_e32 v39, v27
	v_rcp_f32_e32 v41, v37
	v_rcp_f32_e32 v43, v36
	v_mov_b32_e32 v34, v15
	v_mov_b32_e32 v38, v15
	v_pk_mul_f32 v[10:11], v[34:35], v[10:11]
	v_pk_mul_f32 v[22:23], v[38:39], v[22:23]
	v_pk_mul_f32 v[28:29], v[40:41], v[28:29]
	v_pk_mul_f32 v[30:31], v[42:43], v[30:31]
	v_mov_b32_e32 v36, v15
	s_waitcnt vmcnt(41)
	v_mul_f32_e32 v4, v82, v10
	v_mul_f32_e32 v5, v83, v22
	v_mul_f32_e32 v6, v84, v28
	v_mul_f32_e32 v7, v85, v30
	v_mul_f32_e32 v4, v4, v11
	v_mul_f32_e32 v5, v5, v23
	v_mul_f32_e32 v6, v6, v29
	v_mul_f32_e32 v7, v7, v31
	v_cvt_pk_bf16_f32 v4, v4, v5
	v_cvt_pk_bf16_f32 v5, v6, v7
	global_store_dwordx2 v[8:9], v[4:5], off
	ds_read2_b64 v[4:7], v26 offset0:24 offset1:28
	v_lshlrev_b32_e32 v29, 16, v79
	v_lshl_add_u64 v[22:23], v[12:13], 0, v[24:25]
	v_lshlrev_b32_e32 v25, 16, v78
	v_and_b32_e32 v31, 0xffff0000, v79
	s_waitcnt lgkmcnt(0)
	v_lshlrev_b32_e32 v28, 16, v5
	v_and_b32_e32 v30, 0xffff0000, v5
	v_and_b32_e32 v5, 0xffff0000, v78
	v_mul_f32_e32 v27, 0xbfb8aa3b, v5
	v_mul_f32_e32 v32, 0xbfb8aa3b, v29
	v_mul_f32_e32 v14, 0xbfb8aa3b, v25
	v_mul_f32_e32 v33, 0xbfb8aa3b, v31
	v_exp_f32_e32 v27, v27
	v_exp_f32_e32 v32, v32
	v_exp_f32_e32 v14, v14
	v_exp_f32_e32 v33, v33
	v_add_f32_e32 v27, 1.0, v27
	v_add_f32_e32 v32, 1.0, v32
	v_add_f32_e32 v14, 1.0, v14
	v_add_f32_e32 v33, 1.0, v33
	v_rcp_f32_e32 v37, v27
	v_rcp_f32_e32 v39, v32
	v_rcp_f32_e32 v35, v14
	v_rcp_f32_e32 v41, v33
	v_lshlrev_b32_e32 v24, 16, v4
	v_and_b32_e32 v4, 0xffff0000, v4
	v_pk_mul_f32 v[4:5], v[36:37], v[4:5]
	v_pk_mul_f32 v[28:29], v[38:39], v[28:29]
	v_pk_mul_f32 v[24:25], v[34:35], v[24:25]
	v_pk_mul_f32 v[30:31], v[40:41], v[30:31]
	v_mov_b32_e32 v32, v15
	s_waitcnt vmcnt(41)
	v_mul_f32_e32 v4, v87, v4
	v_mul_f32_e32 v9, v88, v28
	v_mul_f32_e32 v8, v86, v24
	v_mul_f32_e32 v10, v89, v30
	v_mul_f32_e32 v4, v4, v5
	v_mul_f32_e32 v5, v9, v29
	v_mul_f32_e32 v8, v8, v25
	v_mul_f32_e32 v9, v10, v31
	v_cvt_pk_bf16_f32 v4, v8, v4
	v_cvt_pk_bf16_f32 v5, v5, v9
	global_store_dwordx2 v[22:23], v[4:5], off
	v_or_b32_e32 v10, 0x100, v2
	v_mov_b32_e32 v11, v3
	v_lshl_add_u64 v[4:5], v[16:17], 0, v[10:11]
	v_lshlrev_b32_e32 v28, 16, v7
	v_and_b32_e32 v30, 0xffff0000, v7
	v_lshlrev_b32_e32 v5, 16, v80
	v_and_b32_e32 v7, 0xffff0000, v80
	v_lshlrev_b32_e32 v29, 16, v81
	v_and_b32_e32 v31, 0xffff0000, v81
	v_mul_f32_e32 v14, 0xbfb8aa3b, v5
	v_mul_f32_e32 v20, 0xbfb8aa3b, v7
	v_mul_f32_e32 v21, 0xbfb8aa3b, v29
	v_mul_f32_e32 v27, 0xbfb8aa3b, v31
	v_exp_f32_e32 v14, v14
	v_exp_f32_e32 v20, v20
	v_exp_f32_e32 v21, v21
	v_exp_f32_e32 v27, v27
	v_add_f32_e32 v14, 1.0, v14
	v_add_f32_e32 v20, 1.0, v20
	v_add_f32_e32 v21, 1.0, v21
	v_add_f32_e32 v27, 1.0, v27
	v_rcp_f32_e32 v33, v14
	v_rcp_f32_e32 v35, v20
	v_rcp_f32_e32 v37, v21
	v_rcp_f32_e32 v39, v27
	v_lshlrev_b32_e32 v4, 16, v6
	v_and_b32_e32 v6, 0xffff0000, v6
	v_pk_mul_f32 v[4:5], v[32:33], v[4:5]
	v_pk_mul_f32 v[6:7], v[34:35], v[6:7]
	v_pk_mul_f32 v[20:21], v[36:37], v[28:29]
	v_pk_mul_f32 v[28:29], v[38:39], v[30:31]
	v_lshl_add_u64 v[36:37], v[12:13], 0, v[10:11]
	s_waitcnt vmcnt(41)
	v_mul_f32_e32 v4, v90, v4
	v_mul_f32_e32 v6, v91, v6
	v_mul_f32_e32 v14, v92, v20
	v_mul_f32_e32 v20, v93, v28
	v_mul_f32_e32 v4, v4, v5
	v_mul_f32_e32 v5, v6, v7
	v_mul_f32_e32 v6, v14, v21
	v_mul_f32_e32 v7, v20, v29
	v_cvt_pk_bf16_f32 v4, v4, v5
	v_cvt_pk_bf16_f32 v5, v6, v7
	global_store_dwordx2 v[18:19], v[4:5], off
	ds_read2_b64 v[28:31], v26 offset0:32 offset1:36
	v_or_b32_e32 v20, 0x120, v2
	v_mov_b32_e32 v21, v3
	v_or_b32_e32 v22, 0x140, v2
	v_mov_b32_e32 v23, v3
	v_or_b32_e32 v18, 0x160, v2
	v_mov_b32_e32 v19, v3
	v_lshl_add_u64 v[24:25], v[16:17], 0, v[20:21]
	v_lshl_add_u64 v[32:33], v[16:17], 0, v[22:23]
	v_lshl_add_u64 v[34:35], v[16:17], 0, v[18:19]
	s_nop 0
	s_nop 0
	s_waitcnt lgkmcnt(0)
	v_lshlrev_b32_e32 v38, 16, v29
	v_and_b32_e32 v40, 0xffff0000, v29
	v_lshlrev_b32_e32 v35, 16, v94
	v_and_b32_e32 v29, 0xffff0000, v94
	v_lshlrev_b32_e32 v39, 16, v95
	v_and_b32_e32 v41, 0xffff0000, v95
	v_mul_f32_e32 v8, 0xbfb8aa3b, v35
	v_mul_f32_e32 v9, 0xbfb8aa3b, v29
	v_mul_f32_e32 v14, 0xbfb8aa3b, v39
	v_mul_f32_e32 v27, 0xbfb8aa3b, v41
	v_exp_f32_e32 v8, v8
	v_exp_f32_e32 v9, v9
	v_exp_f32_e32 v14, v14
	v_exp_f32_e32 v27, v27
	v_add_f32_e32 v8, 1.0, v8
	v_add_f32_e32 v9, 1.0, v9
	v_add_f32_e32 v14, 1.0, v14
	v_add_f32_e32 v27, 1.0, v27
	v_rcp_f32_e32 v43, v8
	v_rcp_f32_e32 v45, v9
	v_rcp_f32_e32 v47, v14
	v_rcp_f32_e32 v49, v27
	v_lshlrev_b32_e32 v34, 16, v28
	v_and_b32_e32 v28, 0xffff0000, v28
	v_pk_mul_f32 v[8:9], v[42:43], v[34:35]
	v_pk_mul_f32 v[28:29], v[44:45], v[28:29]
	v_pk_mul_f32 v[34:35], v[46:47], v[38:39]
	v_pk_mul_f32 v[38:39], v[48:49], v[40:41]
	v_mov_b32_e32 v40, v15
	s_waitcnt vmcnt(41)
	v_mul_f32_e32 v4, v96, v8
	v_mul_f32_e32 v5, v97, v28
	v_mul_f32_e32 v6, v98, v34
	v_mul_f32_e32 v7, v99, v38
	v_mul_f32_e32 v4, v4, v9
	v_mul_f32_e32 v5, v5, v29
	v_mul_f32_e32 v6, v6, v35
	v_mul_f32_e32 v7, v7, v39
	v_cvt_pk_bf16_f32 v4, v4, v5
	v_cvt_pk_bf16_f32 v5, v6, v7
	global_store_dwordx2 v[36:37], v[4:5], off
	v_lshl_add_u64 v[8:9], v[12:13], 0, v[20:21]
	v_lshlrev_b32_e32 v21, 16, v100
	v_and_b32_e32 v29, 0xffff0000, v100
	v_lshlrev_b32_e32 v20, 16, v30
	v_and_b32_e32 v28, 0xffff0000, v30
	v_lshlrev_b32_e32 v30, 16, v31
	v_and_b32_e32 v34, 0xffff0000, v31
	v_lshlrev_b32_e32 v31, 16, v101
	v_and_b32_e32 v35, 0xffff0000, v101
	v_mul_f32_e32 v14, 0xbfb8aa3b, v21
	v_mul_f32_e32 v24, 0xbfb8aa3b, v29
	v_mul_f32_e32 v25, 0xbfb8aa3b, v31
	v_mul_f32_e32 v27, 0xbfb8aa3b, v35
	v_exp_f32_e32 v14, v14
	v_exp_f32_e32 v24, v24
	v_exp_f32_e32 v25, v25
	v_exp_f32_e32 v27, v27
	v_add_f32_e32 v14, 1.0, v14
	v_add_f32_e32 v24, 1.0, v24
	v_add_f32_e32 v25, 1.0, v25
	v_add_f32_e32 v27, 1.0, v27
	v_rcp_f32_e32 v37, v14
	v_rcp_f32_e32 v39, v24
	v_rcp_f32_e32 v41, v25
	v_rcp_f32_e32 v43, v27
	v_mov_b32_e32 v36, v15
	v_mov_b32_e32 v38, v15
	v_pk_mul_f32 v[20:21], v[36:37], v[20:21]
	v_pk_mul_f32 v[24:25], v[38:39], v[28:29]
	v_pk_mul_f32 v[28:29], v[40:41], v[30:31]
	v_pk_mul_f32 v[30:31], v[42:43], v[34:35]
	v_mov_b32_e32 v34, v15
	s_waitcnt vmcnt(41)
	v_mul_f32_e32 v4, v106, v20
	v_mul_f32_e32 v5, v107, v24
	v_mul_f32_e32 v6, v108, v28
	v_mul_f32_e32 v7, v109, v30
	v_mul_f32_e32 v4, v4, v21
	v_mul_f32_e32 v5, v5, v25
	v_mul_f32_e32 v6, v6, v29
	v_mul_f32_e32 v7, v7, v31
	v_cvt_pk_bf16_f32 v4, v4, v5
	v_cvt_pk_bf16_f32 v5, v6, v7
	global_store_dwordx2 v[8:9], v[4:5], off
	ds_read2_b64 v[4:7], v26 offset0:40 offset1:44
	v_lshl_add_u64 v[8:9], v[12:13], 0, v[22:23]
	v_lshlrev_b32_e32 v21, 16, v102
	v_lshlrev_b32_e32 v23, 16, v103
	v_and_b32_e32 v25, 0xffff0000, v103
	s_waitcnt lgkmcnt(0)
	v_lshlrev_b32_e32 v22, 16, v5
	v_and_b32_e32 v24, 0xffff0000, v5
	v_and_b32_e32 v5, 0xffff0000, v102
	v_mul_f32_e32 v14, 0xbfb8aa3b, v21
	v_mul_f32_e32 v27, 0xbfb8aa3b, v5
	v_mul_f32_e32 v32, 0xbfb8aa3b, v23
	v_mul_f32_e32 v33, 0xbfb8aa3b, v25
	v_exp_f32_e32 v14, v14
	v_exp_f32_e32 v27, v27
	v_exp_f32_e32 v32, v32
	v_exp_f32_e32 v33, v33
	v_add_f32_e32 v14, 1.0, v14
	v_add_f32_e32 v27, 1.0, v27
	v_add_f32_e32 v32, 1.0, v32
	v_add_f32_e32 v33, 1.0, v33
	v_rcp_f32_e32 v35, v14
	v_rcp_f32_e32 v37, v27
	v_rcp_f32_e32 v39, v32
	v_rcp_f32_e32 v41, v33
	v_lshlrev_b32_e32 v20, 16, v4
	v_and_b32_e32 v4, 0xffff0000, v4
	v_pk_mul_f32 v[20:21], v[34:35], v[20:21]
	v_pk_mul_f32 v[4:5], v[36:37], v[4:5]
	v_pk_mul_f32 v[22:23], v[38:39], v[22:23]
	v_pk_mul_f32 v[24:25], v[40:41], v[24:25]
	v_mov_b32_e32 v32, v15
	s_waitcnt vmcnt(41)
	v_mul_f32_e32 v14, v120, v20
	v_mul_f32_e32 v4, v121, v4
	v_mul_f32_e32 v20, v122, v22
	v_mul_f32_e32 v22, v123, v24
	v_mul_f32_e32 v4, v4, v5
	v_mul_f32_e32 v5, v20, v23
	v_mul_f32_e32 v14, v14, v21
	v_mul_f32_e32 v20, v22, v25
	v_cvt_pk_bf16_f32 v4, v14, v4
	v_cvt_pk_bf16_f32 v5, v5, v20
	global_store_dwordx2 v[8:9], v[4:5], off
	v_or_b32_e32 v20, 0x180, v2
	v_mov_b32_e32 v21, v3
	v_lshl_add_u64 v[4:5], v[16:17], 0, v[20:21]
	v_lshl_add_u64 v[8:9], v[12:13], 0, v[18:19]
	v_lshlrev_b32_e32 v28, 16, v7
	v_and_b32_e32 v30, 0xffff0000, v7
	v_lshlrev_b32_e32 v5, 16, v104
	v_and_b32_e32 v7, 0xffff0000, v104
	v_lshlrev_b32_e32 v29, 16, v105
	v_and_b32_e32 v31, 0xffff0000, v105
	v_mul_f32_e32 v10, 0xbfb8aa3b, v5
	v_mul_f32_e32 v11, 0xbfb8aa3b, v7
	v_mul_f32_e32 v14, 0xbfb8aa3b, v29
	v_mul_f32_e32 v27, 0xbfb8aa3b, v31
	v_exp_f32_e32 v10, v10
	v_exp_f32_e32 v11, v11
	v_exp_f32_e32 v14, v14
	v_exp_f32_e32 v27, v27
	v_add_f32_e32 v10, 1.0, v10
	v_add_f32_e32 v11, 1.0, v11
	v_add_f32_e32 v14, 1.0, v14
	v_add_f32_e32 v27, 1.0, v27
	v_rcp_f32_e32 v33, v10
	v_rcp_f32_e32 v35, v11
	v_rcp_f32_e32 v37, v14
	v_rcp_f32_e32 v39, v27
	v_lshlrev_b32_e32 v4, 16, v6
	v_and_b32_e32 v6, 0xffff0000, v6
	v_pk_mul_f32 v[4:5], v[32:33], v[4:5]
	v_pk_mul_f32 v[6:7], v[34:35], v[6:7]
	v_pk_mul_f32 v[10:11], v[36:37], v[28:29]
	v_pk_mul_f32 v[28:29], v[38:39], v[30:31]
	v_lshl_add_u64 v[20:21], v[12:13], 0, v[20:21]
	s_waitcnt vmcnt(41)
	v_mul_f32_e32 v4, v124, v4
	v_mul_f32_e32 v6, v125, v6
	v_mul_f32_e32 v10, v126, v10
	v_mul_f32_e32 v14, v127, v28
	v_mul_f32_e32 v4, v4, v5
	v_mul_f32_e32 v5, v6, v7
	v_mul_f32_e32 v6, v10, v11
	v_mul_f32_e32 v7, v14, v29
	v_cvt_pk_bf16_f32 v4, v4, v5
	v_cvt_pk_bf16_f32 v5, v6, v7
	global_store_dwordx2 v[8:9], v[4:5], off
	ds_read2_b64 v[8:11], v26 offset0:48 offset1:52
	v_lshlrev_b32_e32 v33, 16, v110
	v_lshlrev_b32_e32 v35, 16, v111
	v_and_b32_e32 v37, 0xffff0000, v111
	v_mul_f32_e32 v14, 0xbfb8aa3b, v33
	s_waitcnt lgkmcnt(0)
	v_lshlrev_b32_e32 v34, 16, v9
	v_and_b32_e32 v36, 0xffff0000, v9
	v_and_b32_e32 v9, 0xffff0000, v110
	v_mul_f32_e32 v18, 0xbfb8aa3b, v9
	v_mul_f32_e32 v19, 0xbfb8aa3b, v35
	v_mul_f32_e32 v27, 0xbfb8aa3b, v37
	v_exp_f32_e32 v14, v14
	v_exp_f32_e32 v18, v18
	v_or_b32_e32 v22, 0x1a0, v2
	v_mov_b32_e32 v23, v3
	v_or_b32_e32 v24, 0x1c0, v2
	v_mov_b32_e32 v25, v3
	v_or_b32_e32 v2, 0x1e0, v2
	v_exp_f32_e32 v19, v19
	v_exp_f32_e32 v27, v27
	v_lshl_add_u64 v[28:29], v[16:17], 0, v[22:23]
	v_lshl_add_u64 v[30:31], v[16:17], 0, v[24:25]
	v_lshl_add_u64 v[16:17], v[16:17], 0, v[2:3]
	s_nop 0
	s_nop 0
	v_add_f32_e32 v14, 1.0, v14
	v_add_f32_e32 v18, 1.0, v18
	v_add_f32_e32 v19, 1.0, v19
	v_add_f32_e32 v27, 1.0, v27
	v_rcp_f32_e32 v39, v14
	v_rcp_f32_e32 v41, v18
	v_rcp_f32_e32 v43, v19
	v_rcp_f32_e32 v45, v27
	v_lshlrev_b32_e32 v32, 16, v8
	v_and_b32_e32 v8, 0xffff0000, v8
	v_pk_mul_f32 v[18:19], v[38:39], v[32:33]
	v_pk_mul_f32 v[8:9], v[40:41], v[8:9]
	v_pk_mul_f32 v[32:33], v[42:43], v[34:35]
	v_pk_mul_f32 v[34:35], v[44:45], v[36:37]
	v_mov_b32_e32 v36, v15
	v_mov_b32_e32 v42, v0
	s_waitcnt vmcnt(41)
	v_mul_f32_e32 v4, v132, v18
	v_mul_f32_e32 v5, v133, v8
	v_mul_f32_e32 v6, v134, v32
	v_mul_f32_e32 v7, v135, v34
	v_mul_f32_e32 v4, v4, v19
	v_mul_f32_e32 v5, v5, v9
	v_mul_f32_e32 v6, v6, v33
	v_mul_f32_e32 v7, v7, v35
	v_cvt_pk_bf16_f32 v4, v4, v5
	v_cvt_pk_bf16_f32 v5, v6, v7
	global_store_dwordx2 v[20:21], v[4:5], off
	v_lshl_add_u64 v[8:9], v[12:13], 0, v[22:23]
	v_lshlrev_b32_e32 v20, 16, v11
	v_and_b32_e32 v22, 0xffff0000, v11
	v_lshlrev_b32_e32 v18, 16, v10
	v_and_b32_e32 v10, 0xffff0000, v10
	v_mov_b32_e32 v32, v15
	v_mov_b32_e32 v34, v15
	v_lshlrev_b32_e32 v19, 16, v136
	v_and_b32_e32 v11, 0xffff0000, v136
	v_lshlrev_b32_e32 v21, 16, v137
	v_and_b32_e32 v23, 0xffff0000, v137
	v_mul_f32_e32 v14, 0xbfb8aa3b, v19
	v_mul_f32_e32 v27, 0xbfb8aa3b, v11
	v_mul_f32_e32 v28, 0xbfb8aa3b, v21
	v_mul_f32_e32 v29, 0xbfb8aa3b, v23
	v_exp_f32_e32 v14, v14
	v_exp_f32_e32 v27, v27
	v_exp_f32_e32 v28, v28
	v_exp_f32_e32 v29, v29
	v_add_f32_e32 v14, 1.0, v14
	v_add_f32_e32 v27, 1.0, v27
	v_add_f32_e32 v28, 1.0, v28
	v_add_f32_e32 v29, 1.0, v29
	v_rcp_f32_e32 v33, v14
	v_rcp_f32_e32 v35, v27
	v_rcp_f32_e32 v37, v28
	v_rcp_f32_e32 v39, v29
	v_pk_mul_f32 v[18:19], v[32:33], v[18:19]
	v_pk_mul_f32 v[10:11], v[34:35], v[10:11]
	v_pk_mul_f32 v[20:21], v[36:37], v[20:21]
	v_pk_mul_f32 v[22:23], v[38:39], v[22:23]
	v_mov_b32_e32 v28, v15
	s_waitcnt vmcnt(39)
	v_mul_f32_e32 v4, v142, v18
	v_mul_f32_e32 v5, v143, v10
	v_mul_f32_e32 v6, v144, v20
	v_mul_f32_e32 v7, v145, v22
	v_mul_f32_e32 v4, v4, v19
	v_mul_f32_e32 v5, v5, v11
	v_mul_f32_e32 v6, v6, v21
	v_mul_f32_e32 v7, v7, v23
	v_cvt_pk_bf16_f32 v4, v4, v5
	v_cvt_pk_bf16_f32 v5, v6, v7
	global_store_dwordx2 v[8:9], v[4:5], off
	ds_read2_b64 v[4:7], v26 offset0:56 offset1:60
	v_lshl_add_u64 v[18:19], v[12:13], 0, v[24:25]
	v_lshlrev_b32_e32 v23, 16, v139
	v_lshlrev_b32_e32 v21, 16, v138
	v_and_b32_e32 v25, 0xffff0000, v139
	s_waitcnt lgkmcnt(0)
	v_lshlrev_b32_e32 v22, 16, v5
	v_and_b32_e32 v24, 0xffff0000, v5
	v_and_b32_e32 v5, 0xffff0000, v138
	v_mul_f32_e32 v27, 0xbfb8aa3b, v5
	v_mul_f32_e32 v29, 0xbfb8aa3b, v23
	v_mul_f32_e32 v14, 0xbfb8aa3b, v21
	v_mul_f32_e32 v30, 0xbfb8aa3b, v25
	v_exp_f32_e32 v27, v27
	v_exp_f32_e32 v29, v29
	v_exp_f32_e32 v14, v14
	v_exp_f32_e32 v30, v30
	v_add_f32_e32 v31, 1.0, v27
	v_add_f32_e32 v33, 1.0, v29
	v_add_f32_e32 v14, 1.0, v14
	v_add_f32_e32 v30, 1.0, v30
	v_rcp_f32_e32 v29, v31
	v_rcp_f32_e32 v33, v33
	v_rcp_f32_e32 v27, v14
	v_rcp_f32_e32 v35, v30
	v_lshlrev_b32_e32 v20, 16, v4
	v_and_b32_e32 v4, 0xffff0000, v4
	v_mov_b32_e32 v26, v15
	v_pk_mul_f32 v[4:5], v[28:29], v[4:5]
	v_pk_mul_f32 v[22:23], v[32:33], v[22:23]
	v_pk_mul_f32 v[20:21], v[26:27], v[20:21]
	v_pk_mul_f32 v[24:25], v[34:35], v[24:25]
	v_lshlrev_b32_e32 v14, 16, v7
	s_waitcnt vmcnt(39)
	v_mul_f32_e32 v4, v147, v4
	v_mul_f32_e32 v9, v148, v22
	v_mul_f32_e32 v8, v146, v20
	v_mul_f32_e32 v10, v149, v24
	v_mul_f32_e32 v4, v4, v5
	v_mul_f32_e32 v5, v9, v23
	v_mul_f32_e32 v8, v8, v21
	v_mul_f32_e32 v9, v10, v25
	v_cvt_pk_bf16_f32 v4, v8, v4
	v_cvt_pk_bf16_f32 v5, v5, v9
	global_store_dwordx2 v[18:19], v[4:5], off
	v_lshl_add_u64 v[4:5], v[12:13], 0, v[2:3]
	v_and_b32_e32 v18, 0xffff0000, v7
	v_mov_b32_e32 v20, v15
	v_mov_b32_e32 v22, v15
	v_mov_b32_e32 v24, v15
	v_lshlrev_b32_e32 v13, 16, v140
	v_and_b32_e32 v7, 0xffff0000, v140
	v_lshlrev_b32_e32 v15, 16, v141
	v_and_b32_e32 v19, 0xffff0000, v141
	v_mul_f32_e32 v2, 0xbfb8aa3b, v13
	v_mul_f32_e32 v16, 0xbfb8aa3b, v7
	v_mul_f32_e32 v17, 0xbfb8aa3b, v15
	v_mul_f32_e32 v21, 0xbfb8aa3b, v19
	v_exp_f32_e32 v2, v2
	v_exp_f32_e32 v16, v16
	v_exp_f32_e32 v17, v17
	v_exp_f32_e32 v21, v21
	v_add_f32_e32 v2, 1.0, v2
	v_add_f32_e32 v16, 1.0, v16
	v_add_f32_e32 v17, 1.0, v17
	v_add_f32_e32 v27, 1.0, v21
	v_rcp_f32_e32 v21, v2
	v_rcp_f32_e32 v23, v16
	v_rcp_f32_e32 v25, v17
	v_rcp_f32_e32 v27, v27
	v_lshlrev_b32_e32 v12, 16, v6
	v_and_b32_e32 v6, 0xffff0000, v6
	v_pk_mul_f32 v[12:13], v[20:21], v[12:13]
	v_pk_mul_f32 v[6:7], v[22:23], v[6:7]
	v_pk_mul_f32 v[14:15], v[24:25], v[14:15]
	v_pk_mul_f32 v[16:17], v[26:27], v[18:19]
	v_readlane_b32 s4, v244, 32
	v_readlane_b32 s14, v244, 42
	v_readlane_b32 s15, v244, 43
	v_readlane_b32 s16, v244, 44
	v_readlane_b32 s17, v244, 45
	v_readlane_b32 s6, v244, 34
	s_mov_b32 s6, 0xbfb8aa3b
	s_mov_b32 s4, 0x3f2aaaab
	v_readlane_b32 s5, v244, 33
	s_mov_b32 s5, 0x3f317218
	v_readlane_b32 s7, v244, 35
	v_readlane_b32 s8, v244, 36
	v_readlane_b32 s9, v244, 37
	v_readlane_b32 s10, v244, 38
	v_readlane_b32 s11, v244, 39
	v_readlane_b32 s12, v244, 40
	v_readlane_b32 s13, v244, 41
	v_readlane_b32 s18, v244, 46
	v_readlane_b32 s19, v244, 47
	s_waitcnt vmcnt(39)
	v_mul_f32_e32 v2, v150, v12
	v_mul_f32_e32 v6, v151, v6
	v_mul_f32_e32 v8, v152, v14
	v_mul_f32_e32 v9, v153, v16
	v_mul_f32_e32 v6, v6, v7
	v_mul_f32_e32 v7, v8, v15
	v_mul_f32_e32 v2, v2, v13
	v_mul_f32_e32 v8, v9, v17
	v_cvt_pk_bf16_f32 v6, v2, v6
	v_cvt_pk_bf16_f32 v7, v7, v8
	global_store_dwordx2 v[4:5], v[6:7], off
	s_barrier
	s_waitcnt vmcnt(32)
	s_nop 0
	v_ashrrev_i32_e32 v43, 31, v42
	v_lshlrev_b64 v[4:5], 2, v[42:43]
	v_lshl_add_u64 v[6:7], s[42:43], 0, v[4:5]
	v_mov_b32_e32 v2, v154
	v_lshl_add_u64 v[8:9], s[14:15], 0, v[4:5]
	v_add_co_u32_e32 v6, vcc, s0, v8
	v_bfe_u32 v43, v42, 4, 2
	s_nop 0
	v_addc_co_u32_e32 v7, vcc, 0, v9, vcc
	v_mov_b32_e32 v14, v155
	v_mov_b32_e32 v15, v168
	v_mov_b32_e32 v16, v169
	v_mov_b32_e32 v17, v171
	v_and_b32_e32 v18, 0xffffffc0, v42
	v_lshl_or_b32 v104, v43, 3, v18
	v_lshl_add_u64 v[18:19], s[16:17], 0, v[4:5]
	v_lshl_add_u64 v[20:21], s[36:37], 0, v[4:5]
	v_lshl_add_u64 v[4:5], s[40:41], 0, v[4:5]
	v_mov_b32_e32 v18, v240
	s_nop 0
	v_mov_b32_e32 v19, v241
	s_nop 0
	v_mov_b32_e32 v20, v242
	v_lshl_add_u32 v30, v42, 5, 0
	v_and_b32_e32 v195, 15, v42
	v_cmp_lt_u32_e32 vcc, 2, v195
	s_or_b64 s[0:1], s[22:23], vcc
	v_mov_b32_e32 v8, v3
	v_mov_b32_e32 v9, v3
	v_mov_b32_e32 v6, v3
	v_mov_b32_e32 v7, v3
	v_mov_b64_e32 v[12:13], v[8:9]
	v_mov_b64_e32 v[10:11], v[6:7]
	v_ashrrev_i32_e32 v105, 31, v104
	v_mul_f32_e64 v4, |v2|, s6
	v_exp_f32_e32 v21, v4
	v_max_f32_e64 v2, -v2, -v2
	v_max_f32_e32 v2, 0, v2
	ds_write_b128 v30, v[14:17]
	v_add_f32_e32 v14, 1.0, v21
	v_add_f32_e32 v15, -1.0, v14
	v_frexp_mant_f32_e32 v16, v14
	v_cvt_f64_f32_e32 v[4:5], v14
	v_sub_f32_e32 v17, v15, v14
	v_frexp_exp_i32_f64_e32 v4, v[4:5]
	v_cmp_gt_f32_e32 vcc, s4, v16
	v_sub_f32_e32 v15, v21, v15
	v_add_f32_e32 v5, 1.0, v17
	v_subbrev_co_u32_e32 v4, vcc, 0, v4, vcc
	v_add_f32_e32 v5, v15, v5
	v_sub_u32_e32 v15, 0, v4
	v_ldexp_f32 v14, v14, v15
	v_add_f32_e32 v16, -1.0, v14
	v_add_f32_e32 v17, 1.0, v14
	v_ldexp_f32 v5, v5, v15
	v_add_f32_e32 v15, 1.0, v16
	v_add_f32_e32 v22, -1.0, v17
	v_sub_f32_e32 v15, v14, v15
	v_sub_f32_e32 v14, v14, v22
	v_add_f32_e32 v22, v5, v15
	v_add_f32_e32 v5, v5, v14
	v_add_f32_e32 v24, v17, v5
	v_rcp_f32_e32 v25, v24
	v_add_f32_e32 v15, v16, v22
	v_sub_f32_e32 v16, v15, v16
	v_sub_f32_e32 v14, v24, v17
	v_mul_f32_e32 v27, v15, v25
	v_sub_f32_e32 v26, v22, v16
	v_mul_f32_e32 v16, v24, v27
	v_sub_f32_e32 v5, v5, v14
	v_fma_f32 v22, v27, v24, -v16
	v_fmac_f32_e32 v22, v27, v5
	v_add_f32_e32 v14, v16, v22
	v_sub_f32_e32 v17, v15, v14
	v_mov_b32_e32 v23, v14
	v_pk_add_f32 v[14:15], v[14:15], v[16:17] neg_lo:[0,1] neg_hi:[0,1]
	v_cvt_f32_i32_e32 v4, v4
	v_pk_add_f32 v[14:15], v[14:15], v[22:23] neg_lo:[0,1] neg_hi:[0,1]
	v_cmp_neq_f32_e32 vcc, s3, v21
	v_add_f32_e32 v15, v26, v15
	v_add_f32_e32 v14, v14, v15
	v_add_f32_e32 v15, v17, v14
	v_mul_f32_e32 v23, v25, v15
	v_mul_f32_e32 v16, v24, v23
	v_sub_f32_e32 v17, v17, v15
	v_add_f32_e32 v28, v27, v23
	v_fma_f32 v22, v23, v24, -v16
	v_add_f32_e32 v26, v14, v17
	v_sub_f32_e32 v14, v28, v27
	v_fmac_f32_e32 v22, v23, v5
	v_sub_f32_e32 v5, v23, v14
	v_add_f32_e32 v14, v16, v22
	v_sub_f32_e32 v17, v15, v14
	v_mov_b32_e32 v23, v14
	v_pk_add_f32 v[14:15], v[14:15], v[16:17] neg_lo:[0,1] neg_hi:[0,1]
	s_nop 0
	v_pk_add_f32 v[14:15], v[14:15], v[22:23] neg_lo:[0,1] neg_hi:[0,1]
	s_nop 0
	v_add_f32_e32 v15, v26, v15
	v_add_f32_e32 v14, v14, v15
	v_add_f32_e32 v14, v17, v14
	v_mul_f32_e32 v14, v25, v14
	v_add_f32_e32 v5, v5, v14
	v_add_f32_e32 v14, v28, v5
	v_mul_f32_e32 v16, v14, v14
	v_sub_f32_e32 v17, v14, v28
	v_fmamk_f32 v22, v16, 0x3e9b6dac, v181
	v_sub_f32_e32 v17, v5, v17
	v_mul_f32_e32 v5, v14, v16
	v_fmaak_f32 v113, v16, v22, 0x3f2aaada
	v_ldexp_f32 v23, v17, 1
	v_pk_mul_f32 v[16:17], v[4:5], v[112:113]
	v_ldexp_f32 v15, v14, 1
	v_fma_f32 v14, v4, s5, -v16
	v_fmac_f32_e32 v14, 0xb102e308, v4
	v_pk_add_f32 v[4:5], v[16:17], v[14:15]
	v_mov_b32_e32 v22, v16
	v_sub_f32_e32 v26, v5, v15
	v_pk_add_f32 v[24:25], v[4:5], v[16:17] neg_lo:[0,1] neg_hi:[0,1]
	v_sub_f32_e32 v16, v17, v26
	v_add_f32_e32 v23, v23, v16
	v_pk_add_f32 v[16:17], v[4:5], v[22:23]
	v_mov_b32_e32 v15, v4
	v_mov_b32_e32 v25, v17
	v_pk_add_f32 v[28:29], v[14:15], v[24:25] neg_lo:[0,1] neg_hi:[0,1]
	v_pk_add_f32 v[14:15], v[14:15], v[24:25]
	v_mov_b32_e32 v27, v4
	v_pk_add_f32 v[24:25], v[14:15], v[4:5] op_sel:[1,0] op_sel_hi:[0,1] neg_lo:[0,1] neg_hi:[0,1]
	v_mov_b32_e32 v26, v23
	v_mov_b32_e32 v22, v17
	v_mov_b32_e32 v23, v15
	v_pk_mov_b32 v[4:5], v[4:5], v[24:25] op_sel:[1,0]
	v_pk_add_f32 v[16:17], v[16:17], v[24:25] op_sel_hi:[1,0] neg_lo:[0,1] neg_hi:[0,1]
	v_pk_add_f32 v[4:5], v[22:23], v[4:5] neg_lo:[0,1] neg_hi:[0,1]
	v_mov_b32_e32 v16, v28
	v_pk_add_f32 v[4:5], v[26:27], v[4:5] neg_lo:[0,1] neg_hi:[0,1]
	v_mov_b32_e32 v29, v15
	v_pk_add_f32 v[16:17], v[16:17], v[4:5]
	s_nop 0
	v_pk_add_f32 v[22:23], v[16:17], v[16:17] op_sel:[0,1] op_sel_hi:[1,0]
	s_nop 0
	v_pk_add_f32 v[14:15], v[14:15], v[22:23] op_sel:[1,0] op_sel_hi:[0,1]
	v_mov_b32_e32 v17, v14
	v_mov_b32_e32 v5, v22
	v_pk_add_f32 v[22:23], v[16:17], v[28:29] neg_lo:[0,1] neg_hi:[0,1]
	s_nop 0
	v_sub_f32_e32 v15, v16, v22
	v_pk_add_f32 v[4:5], v[4:5], v[22:23] neg_lo:[0,1] neg_hi:[0,1]
	v_sub_f32_e32 v15, v28, v15
	v_add_f32_e32 v4, v4, v15
	v_add_f32_e32 v4, v4, v5
	v_add_f32_e32 v4, v14, v4
	v_cndmask_b32_e32 v4, v185, v4, vcc
	v_cmp_ngt_f32_e32 vcc, -1.0, v21
	v_mov_b64_e32 v[16:17], v[8:9]
	v_mov_b64_e32 v[14:15], v[6:7]
	v_cndmask_b32_e32 v4, v186, v4, vcc
	v_cmp_neq_f32_e32 vcc, -1.0, v21
	s_nop 1
	v_cndmask_b32_e32 v4, v187, v4, vcc
	v_cmp_lt_f32_e64 vcc, |v21|, s2
	s_nop 1
	v_cndmask_b32_e32 v4, v4, v21, vcc
	v_add_f32_e32 v2, v2, v4
	v_mul_f32_e32 v21, 0xc1000000, v2
	ds_write_b128 v30, v[18:21] offset:16
	s_and_saveexec_b64 s[2:3], s[0:1]
	s_cbranch_execz .LBB0_217
	v_add3_u32 v2, s20, -3, v195
	v_mov_b64_e32 v[4:5], s[88:89]
	v_mad_i64_i32 v[4:5], s[0:1], v2, s92, v[4:5]
	v_lshl_add_u64 v[4:5], v[104:105], 1, v[4:5]
	global_load_dwordx4 v[14:17], v[4:5], off
	global_load_dwordx4 v[10:13], v[4:5], off offset:64

.LBB0_222:
	s_mov_b32 s4, 0x3fb8aa3b
	v_pk_fma_f32 v[38:39], v[100:101], s[4:5], v[108:109] op_sel_hi:[1,0,1] neg_lo:[1,0,0] neg_hi:[1,0,0]
	s_mov_b32 s6, 0x3fb17218
	v_exp_f32_e32 v38, v38
	v_exp_f32_e32 v39, v39
	s_mov_b32 s0, 0x3d2aaaab
	s_mov_b32 s8, 0x3e2aaaab
	v_pk_fma_f32 v[40:41], v[96:97], s[4:5], v[110:111] op_sel_hi:[1,0,1] neg_lo:[1,0,0] neg_hi:[1,0,0]
	v_pk_add_f32 v[38:39], v[38:39], 1.0 op_sel_hi:[1,0]
	v_exp_f32_e32 v40, v40
	v_rcp_f32_e32 v38, v38
	v_rcp_f32_e32 v39, v39
	v_exp_f32_e32 v41, v41
	s_add_i32 s2, s2, 16
	v_pk_mul_f32 v[38:39], v[114:115], v[38:39]
	v_pk_add_f32 v[40:41], v[40:41], 1.0 op_sel_hi:[1,0]
	v_exp_f32_e32 v100, v38
	v_exp_f32_e32 v101, v39
	v_pk_mul_f32 v[42:43], v[38:39], s[6:7] op_sel_hi:[1,0]
	v_mov_b64_e32 v[38:39], s[0:1]
	s_mov_b32 s0, 0x3c088889
	v_pk_fma_f32 v[44:45], v[42:43], s[0:1], v[38:39] op_sel_hi:[1,0,0]
	v_pk_fma_f32 v[46:47], v[100:101], v[100:101], 1.0 op_sel_hi:[1,1,0] neg_lo:[1,0,0] neg_hi:[1,0,0]
	v_pk_fma_f32 v[44:45], v[42:43], v[44:45], s[8:9] op_sel_hi:[1,1,0]
	v_cmp_lt_f32_e32 vcc, s7, v42
	v_pk_fma_f32 v[44:45], v[42:43], v[44:45], 0.5 op_sel_hi:[1,1,0]
	v_rcp_f32_e32 v40, v40
	v_pk_fma_f32 v[44:45], v[42:43], v[44:45], 1.0 op_sel_hi:[1,1,0]
	v_rcp_f32_e32 v41, v41
	v_pk_mul_f32 v[44:45], v[42:43], v[44:45] neg_lo:[0,1] neg_hi:[0,1]
	v_cndmask_b32_e32 v42, v46, v44, vcc
	v_cmp_lt_f32_e32 vcc, s7, v43
	v_pk_mul_f32 v[4:5], v[4:5], v[40:41]
	v_pk_fma_f32 v[40:41], v[92:93], s[4:5], v[122:123] op_sel_hi:[1,0,1] neg_lo:[1,0,0] neg_hi:[1,0,0]
	v_cndmask_b32_e32 v43, v47, v45, vcc
	v_pk_fma_f32 v[44:45], v[102:103], s[4:5], v[116:117] op_sel_hi:[1,0,1] neg_lo:[1,0,0] neg_hi:[1,0,0]
	v_pk_fma_f32 v[46:47], v[98:99], s[4:5], v[118:119] op_sel_hi:[1,0,1] neg_lo:[1,0,0] neg_hi:[1,0,0]
	v_exp_f32_e32 v44, v44
	v_exp_f32_e32 v45, v45
	v_exp_f32_e32 v40, v40
	v_exp_f32_e32 v41, v41
	v_exp_f32_e32 v46, v46
	v_pk_add_f32 v[44:45], v[44:45], 1.0 op_sel_hi:[1,0]
	v_exp_f32_e32 v47, v47
	v_rcp_f32_e32 v44, v44
	v_rcp_f32_e32 v45, v45
	v_pk_add_f32 v[40:41], v[40:41], 1.0 op_sel_hi:[1,0]
	v_pk_add_f32 v[46:47], v[46:47], 1.0 op_sel_hi:[1,0]
	v_rcp_f32_e32 v40, v40
	v_pk_mul_f32 v[44:45], v[120:121], v[44:45]
	v_rcp_f32_e32 v41, v41
	v_exp_f32_e32 v96, v44
	v_exp_f32_e32 v97, v45
	v_pk_mul_f32 v[44:45], v[44:45], s[6:7] op_sel_hi:[1,0]
	v_sqrt_f32_e32 v42, v42
	v_pk_fma_f32 v[48:49], v[44:45], s[0:1], v[38:39] op_sel_hi:[1,0,0]
	v_pk_fma_f32 v[50:51], v[96:97], v[96:97], 1.0 op_sel_hi:[1,1,0] neg_lo:[1,0,0] neg_hi:[1,0,0]
	v_pk_fma_f32 v[48:49], v[44:45], v[48:49], s[8:9] op_sel_hi:[1,1,0]
	v_cmp_lt_f32_e32 vcc, s7, v44
	v_pk_fma_f32 v[48:49], v[44:45], v[48:49], 0.5 op_sel_hi:[1,1,0]
	v_sqrt_f32_e32 v43, v43
	v_pk_fma_f32 v[48:49], v[44:45], v[48:49], 1.0 op_sel_hi:[1,1,0]
	v_rcp_f32_e32 v46, v46
	v_pk_mul_f32 v[48:49], v[44:45], v[48:49] neg_lo:[0,1] neg_hi:[0,1]
	v_rcp_f32_e32 v47, v47
	v_cndmask_b32_e32 v44, v50, v48, vcc
	v_cmp_lt_f32_e32 vcc, s7, v45
	v_sqrt_f32_e32 v44, v44
	v_pk_mul_f32 v[40:41], v[126:127], v[40:41]
	v_cndmask_b32_e32 v45, v51, v49, vcc
	v_sqrt_f32_e32 v45, v45
	v_pk_mul_f32 v[102:103], v[4:5], v[42:43]
	v_pk_mul_f32 v[4:5], v[78:79], v[46:47]
	v_exp_f32_e32 v92, v40
	v_exp_f32_e32 v93, v41
	v_pk_mul_f32 v[40:41], v[40:41], s[6:7] op_sel_hi:[1,0]
	v_pk_mul_f32 v[172:173], v[4:5], v[44:45]
	v_pk_fma_f32 v[44:45], v[40:41], s[0:1], v[38:39] op_sel_hi:[1,0,0]
	v_pk_fma_f32 v[46:47], v[92:93], v[92:93], 1.0 op_sel_hi:[1,1,0] neg_lo:[1,0,0] neg_hi:[1,0,0]
	v_pk_fma_f32 v[44:45], v[40:41], v[44:45], s[8:9] op_sel_hi:[1,1,0]
	v_cmp_lt_f32_e32 vcc, s7, v40
	v_pk_fma_f32 v[44:45], v[40:41], v[44:45], 0.5 op_sel_hi:[1,1,0]
	v_mov_b32_e32 v78, v173
	v_pk_fma_f32 v[44:45], v[40:41], v[44:45], 1.0 op_sel_hi:[1,1,0]
	v_mov_b32_e32 v4, v101
	v_pk_mul_f32 v[44:45], v[40:41], v[44:45] neg_lo:[0,1] neg_hi:[0,1]
	v_mov_b32_e32 v5, v96
	v_cndmask_b32_e32 v40, v46, v44, vcc
	v_cmp_lt_f32_e32 vcc, s7, v41
	s_nop 1
v_fmac_f32_dpp v102, v239, v100 row_shl:15 row_mask:0xf bank_mask:0xf
 v_fmac_f32_dpp v103, v240, v4 row_shl:15 row_mask:0xf bank_mask:0xf
v_fmac_f32_dpp v172, v241, v5 row_shl:15 row_mask:0xf bank_mask:0xf
 v_fmac_f32_dpp v78, v242, v97 row_shl:15 row_mask:0xf bank_mask:0xf
v_mul_f32_dpp v100, v179, v100 row_shl:15 row_mask:0xf bank_mask:0xf
 v_mul_f32_dpp v4, v236, v4 row_shl:15 row_mask:0xf bank_mask:0xf
v_mul_f32_dpp v5, v237, v5 row_shl:15 row_mask:0xf bank_mask:0xf
 v_mul_f32_dpp v97, v238, v97 row_shl:15 row_mask:0xf bank_mask:0xf
v_fmac_f32_dpp v102, v102, v100 row_shr:1 row_mask:0xf bank_mask:0xf
 v_fmac_f32_dpp v103, v103, v4 row_shr:1 row_mask:0xf bank_mask:0xf
v_fmac_f32_dpp v172, v172, v5 row_shr:1 row_mask:0xf bank_mask:0xf
 v_fmac_f32_dpp v78, v78, v97 row_shr:1 row_mask:0xf bank_mask:0xf
v_mul_f32_dpp v100, v100, v100 row_shr:1 row_mask:0xf bank_mask:0xf
 v_mul_f32_dpp v4, v4, v4 row_shr:1 row_mask:0xf bank_mask:0xf
v_mul_f32_dpp v5, v5, v5 row_shr:1 row_mask:0xf bank_mask:0xf
 v_mul_f32_dpp v97, v97, v97 row_shr:1 row_mask:0xf bank_mask:0xf
v_fmac_f32_dpp v102, v102, v100 row_shr:2 row_mask:0xf bank_mask:0xf
 v_fmac_f32_dpp v103, v103, v4 row_shr:2 row_mask:0xf bank_mask:0xf
v_fmac_f32_dpp v172, v172, v5 row_shr:2 row_mask:0xf bank_mask:0xf
 v_fmac_f32_dpp v78, v78, v97 row_shr:2 row_mask:0xf bank_mask:0xf
v_mul_f32_dpp v100, v100, v100 row_shr:2 row_mask:0xf bank_mask:0xf
 v_mul_f32_dpp v4, v4, v4 row_shr:2 row_mask:0xf bank_mask:0xf
v_mul_f32_dpp v5, v5, v5 row_shr:2 row_mask:0xf bank_mask:0xf
 v_mul_f32_dpp v97, v97, v97 row_shr:2 row_mask:0xf bank_mask:0xf
v_fmac_f32_dpp v102, v102, v100 row_shr:4 row_mask:0xf bank_mask:0xf
 v_fmac_f32_dpp v103, v103, v4 row_shr:4 row_mask:0xf bank_mask:0xf
v_fmac_f32_dpp v172, v172, v5 row_shr:4 row_mask:0xf bank_mask:0xf
 v_fmac_f32_dpp v78, v78, v97 row_shr:4 row_mask:0xf bank_mask:0xf
v_mul_f32_dpp v100, v100, v100 row_shr:4 row_mask:0xf bank_mask:0xf
 v_mul_f32_dpp v4, v4, v4 row_shr:4 row_mask:0xf bank_mask:0xf
v_mul_f32_dpp v5, v5, v5 row_shr:4 row_mask:0xf bank_mask:0xf
 v_mul_f32_dpp v97, v97, v97 row_shr:4 row_mask:0xf bank_mask:0xf
v_fmac_f32_dpp v102, v102, v100 row_shr:8 row_mask:0xf bank_mask:0xf
 v_fmac_f32_dpp v103, v103, v4 row_shr:8 row_mask:0xf bank_mask:0xf
v_fmac_f32_dpp v172, v172, v5 row_shr:8 row_mask:0xf bank_mask:0xf
 v_fmac_f32_dpp v78, v78, v97 row_shr:8 row_mask:0xf bank_mask:0xf
v_mul_f32_dpp v100, v100, v100 row_shr:8 row_mask:0xf bank_mask:0xf
 v_mul_f32_dpp v4, v4, v4 row_shr:8 row_mask:0xf bank_mask:0xf
v_mul_f32_dpp v5, v5, v5 row_shr:8 row_mask:0xf bank_mask:0xf
 v_mul_f32_dpp v97, v97, v97 row_shr:8 row_mask:0xf bank_mask:0xf
s_nop 1

	v_pk_fma_f32 v[42:43], v[88:89], s[4:5], v[124:125] op_sel_hi:[1,0,1] neg_lo:[1,0,0] neg_hi:[1,0,0]
	v_sqrt_f32_e32 v40, v40
	v_cndmask_b32_e32 v41, v47, v45, vcc
	v_pk_fma_f32 v[44:45], v[94:95], s[4:5], v[128:129] op_sel_hi:[1,0,1] neg_lo:[1,0,0] neg_hi:[1,0,0]
	v_exp_f32_e32 v42, v42
	v_exp_f32_e32 v44, v44
	v_exp_f32_e32 v45, v45
	v_exp_f32_e32 v43, v43
	v_pk_fma_f32 v[46:47], v[90:91], s[4:5], v[130:131] op_sel_hi:[1,0,1] neg_lo:[1,0,0] neg_hi:[1,0,0]
	v_sqrt_f32_e32 v41, v41
	v_pk_add_f32 v[44:45], v[44:45], 1.0 op_sel_hi:[1,0]
	v_exp_f32_e32 v46, v46
	v_rcp_f32_e32 v44, v44
	v_rcp_f32_e32 v45, v45
	v_exp_f32_e32 v47, v47
	v_pk_add_f32 v[42:43], v[42:43], 1.0 op_sel_hi:[1,0]
	v_mov_b32_e32 v96, v93
	v_pk_mul_f32 v[44:45], v[132:133], v[44:45]
	v_rcp_f32_e32 v42, v42
	v_exp_f32_e32 v178, v44
	v_exp_f32_e32 v179, v45
	v_pk_mul_f32 v[44:45], v[44:45], s[6:7] op_sel_hi:[1,0]
	v_rcp_f32_e32 v43, v43
	v_pk_fma_f32 v[48:49], v[44:45], s[0:1], v[38:39] op_sel_hi:[1,0,0]
	v_pk_fma_f32 v[50:51], v[178:179], v[178:179], 1.0 op_sel_hi:[1,1,0] neg_lo:[1,0,0] neg_hi:[1,0,0]
	v_pk_fma_f32 v[48:49], v[44:45], v[48:49], s[8:9] op_sel_hi:[1,1,0]
	v_cmp_lt_f32_e32 vcc, s7, v44
	v_pk_fma_f32 v[48:49], v[44:45], v[48:49], 0.5 op_sel_hi:[1,1,0]
	v_pk_add_f32 v[46:47], v[46:47], 1.0 op_sel_hi:[1,0]
	v_pk_fma_f32 v[48:49], v[44:45], v[48:49], 1.0 op_sel_hi:[1,1,0]
	v_rcp_f32_e32 v46, v46
	v_pk_mul_f32 v[48:49], v[44:45], v[48:49] neg_lo:[0,1] neg_hi:[0,1]
	v_rcp_f32_e32 v47, v47
	v_cndmask_b32_e32 v44, v50, v48, vcc
	v_cmp_lt_f32_e32 vcc, s7, v45
	v_sqrt_f32_e32 v44, v44
	v_pk_mul_f32 v[42:43], v[174:175], v[42:43]
	v_cndmask_b32_e32 v45, v51, v49, vcc
	v_sqrt_f32_e32 v45, v45
	v_pk_mul_f32 v[98:99], v[42:43], v[40:41]
	v_pk_mul_f32 v[40:41], v[176:177], v[46:47]
	v_pk_fma_f32 v[42:43], v[80:81], s[4:5], v[136:137] op_sel_hi:[1,0,1] neg_lo:[1,0,0] neg_hi:[1,0,0]
	v_pk_mul_f32 v[174:175], v[40:41], v[44:45]
	v_pk_fma_f32 v[40:41], v[84:85], s[4:5], v[134:135] op_sel_hi:[1,0,1] neg_lo:[1,0,0] neg_hi:[1,0,0]
	v_exp_f32_e32 v42, v42
	v_exp_f32_e32 v40, v40
	v_exp_f32_e32 v41, v41
	v_exp_f32_e32 v43, v43
	v_mov_b32_e32 v94, v175
	v_mov_b32_e32 v79, v98
	v_pk_add_f32 v[40:41], v[40:41], 1.0 op_sel_hi:[1,0]
	v_pk_add_f32 v[42:43], v[42:43], 1.0 op_sel_hi:[1,0]
	v_rcp_f32_e32 v40, v40
	v_rcp_f32_e32 v41, v41
	v_rcp_f32_e32 v42, v42
	v_rcp_f32_e32 v43, v43
	v_mov_b32_e32 v98, v179
	v_pk_mul_f32 v[40:41], v[138:139], v[40:41]
	s_nop 1
v_fmac_f32_dpp v79, v232, v92 row_shl:15 row_mask:0xf bank_mask:0xf
 v_fmac_f32_dpp v99, v233, v96 row_shl:15 row_mask:0xf bank_mask:0xf
v_fmac_f32_dpp v174, v234, v178 row_shl:15 row_mask:0xf bank_mask:0xf
 v_fmac_f32_dpp v94, v235, v98 row_shl:15 row_mask:0xf bank_mask:0xf
v_mul_f32_dpp v92, v228, v92 row_shl:15 row_mask:0xf bank_mask:0xf
 v_mul_f32_dpp v96, v229, v96 row_shl:15 row_mask:0xf bank_mask:0xf
v_mul_f32_dpp v178, v230, v178 row_shl:15 row_mask:0xf bank_mask:0xf
 v_mul_f32_dpp v98, v231, v98 row_shl:15 row_mask:0xf bank_mask:0xf
v_fmac_f32_dpp v79, v79, v92 row_shr:1 row_mask:0xf bank_mask:0xf
 v_fmac_f32_dpp v99, v99, v96 row_shr:1 row_mask:0xf bank_mask:0xf
v_fmac_f32_dpp v174, v174, v178 row_shr:1 row_mask:0xf bank_mask:0xf
 v_fmac_f32_dpp v94, v94, v98 row_shr:1 row_mask:0xf bank_mask:0xf
v_mul_f32_dpp v92, v92, v92 row_shr:1 row_mask:0xf bank_mask:0xf
 v_mul_f32_dpp v96, v96, v96 row_shr:1 row_mask:0xf bank_mask:0xf
v_mul_f32_dpp v178, v178, v178 row_shr:1 row_mask:0xf bank_mask:0xf
 v_mul_f32_dpp v98, v98, v98 row_shr:1 row_mask:0xf bank_mask:0xf
v_fmac_f32_dpp v79, v79, v92 row_shr:2 row_mask:0xf bank_mask:0xf
 v_fmac_f32_dpp v99, v99, v96 row_shr:2 row_mask:0xf bank_mask:0xf
v_fmac_f32_dpp v174, v174, v178 row_shr:2 row_mask:0xf bank_mask:0xf
 v_fmac_f32_dpp v94, v94, v98 row_shr:2 row_mask:0xf bank_mask:0xf
v_mul_f32_dpp v92, v92, v92 row_shr:2 row_mask:0xf bank_mask:0xf
 v_mul_f32_dpp v96, v96, v96 row_shr:2 row_mask:0xf bank_mask:0xf
v_mul_f32_dpp v178, v178, v178 row_shr:2 row_mask:0xf bank_mask:0xf
 v_mul_f32_dpp v98, v98, v98 row_shr:2 row_mask:0xf bank_mask:0xf
v_fmac_f32_dpp v79, v79, v92 row_shr:4 row_mask:0xf bank_mask:0xf
 v_fmac_f32_dpp v99, v99, v96 row_shr:4 row_mask:0xf bank_mask:0xf
v_fmac_f32_dpp v174, v174, v178 row_shr:4 row_mask:0xf bank_mask:0xf
 v_fmac_f32_dpp v94, v94, v98 row_shr:4 row_mask:0xf bank_mask:0xf
v_mul_f32_dpp v92, v92, v92 row_shr:4 row_mask:0xf bank_mask:0xf
 v_mul_f32_dpp v96, v96, v96 row_shr:4 row_mask:0xf bank_mask:0xf
v_mul_f32_dpp v178, v178, v178 row_shr:4 row_mask:0xf bank_mask:0xf
 v_mul_f32_dpp v98, v98, v98 row_shr:4 row_mask:0xf bank_mask:0xf
v_fmac_f32_dpp v79, v79, v92 row_shr:8 row_mask:0xf bank_mask:0xf
 v_fmac_f32_dpp v99, v99, v96 row_shr:8 row_mask:0xf bank_mask:0xf
v_fmac_f32_dpp v174, v174, v178 row_shr:8 row_mask:0xf bank_mask:0xf
 v_fmac_f32_dpp v94, v94, v98 row_shr:8 row_mask:0xf bank_mask:0xf
v_mul_f32_dpp v92, v92, v92 row_shr:8 row_mask:0xf bank_mask:0xf
 v_mul_f32_dpp v96, v96, v96 row_shr:8 row_mask:0xf bank_mask:0xf
v_mul_f32_dpp v178, v178, v178 row_shr:8 row_mask:0xf bank_mask:0xf
 v_mul_f32_dpp v98, v98, v98 row_shr:8 row_mask:0xf bank_mask:0xf
s_nop 1

	v_pk_mul_f32 v[42:43], v[162:163], v[42:43]
	v_exp_f32_e32 v80, v40
	v_exp_f32_e32 v81, v41
	v_pk_mul_f32 v[40:41], v[40:41], s[6:7] op_sel_hi:[1,0]
	v_pk_fma_f32 v[44:45], v[40:41], s[0:1], v[38:39] op_sel_hi:[1,0,0]
	v_pk_fma_f32 v[46:47], v[80:81], v[80:81], 1.0 op_sel_hi:[1,1,0] neg_lo:[1,0,0] neg_hi:[1,0,0]
	v_pk_fma_f32 v[44:45], v[40:41], v[44:45], s[8:9] op_sel_hi:[1,1,0]
	v_cmp_lt_f32_e32 vcc, s7, v40
	v_pk_fma_f32 v[44:45], v[40:41], v[44:45], 0.5 op_sel_hi:[1,1,0]
	v_pk_fma_f32 v[44:45], v[40:41], v[44:45], 1.0 op_sel_hi:[1,1,0]
	s_cmpk_eq_i32 s2, 0x80
	v_pk_mul_f32 v[44:45], v[40:41], v[44:45] neg_lo:[0,1] neg_hi:[0,1]
	v_mov_b32_e32 v179, v100
	v_cndmask_b32_e32 v40, v46, v44, vcc
	v_cmp_lt_f32_e32 vcc, s7, v41
	v_sqrt_f32_e32 v40, v40
	v_mov_b32_e32 v236, v4
	v_cndmask_b32_e32 v41, v47, v45, vcc
	v_pk_fma_f32 v[44:45], v[86:87], s[4:5], v[140:141] op_sel_hi:[1,0,1] neg_lo:[1,0,0] neg_hi:[1,0,0]
	v_pk_fma_f32 v[46:47], v[82:83], s[4:5], v[142:143] op_sel_hi:[1,0,1] neg_lo:[1,0,0] neg_hi:[1,0,0]
	v_exp_f32_e32 v44, v44
	v_exp_f32_e32 v45, v45
	v_exp_f32_e32 v46, v46
	v_exp_f32_e32 v47, v47
	v_sqrt_f32_e32 v41, v41
	v_pk_add_f32 v[44:45], v[44:45], 1.0 op_sel_hi:[1,0]
	v_mov_b32_e32 v237, v5
	v_rcp_f32_e32 v44, v44
	v_rcp_f32_e32 v45, v45
	v_pk_add_f32 v[46:47], v[46:47], 1.0 op_sel_hi:[1,0]
	v_pk_mul_f32 v[84:85], v[42:43], v[40:41]
	v_rcp_f32_e32 v46, v46
	v_pk_mul_f32 v[44:45], v[144:145], v[44:45]
	v_rcp_f32_e32 v47, v47
	v_exp_f32_e32 v82, v44
	v_exp_f32_e32 v83, v45
	v_pk_mul_f32 v[44:45], v[44:45], s[6:7] op_sel_hi:[1,0]
	v_pk_mul_f32 v[40:41], v[168:169], v[46:47]
	v_pk_fma_f32 v[48:49], v[44:45], s[0:1], v[38:39] op_sel_hi:[1,0,0]
	v_pk_fma_f32 v[50:51], v[82:83], v[82:83], 1.0 op_sel_hi:[1,1,0] neg_lo:[1,0,0] neg_hi:[1,0,0]
	v_pk_fma_f32 v[48:49], v[44:45], v[48:49], s[8:9] op_sel_hi:[1,1,0]
	v_cmp_lt_f32_e32 vcc, s7, v44
	v_pk_fma_f32 v[48:49], v[44:45], v[48:49], 0.5 op_sel_hi:[1,1,0]
	v_pk_fma_f32 v[42:43], v[70:71], s[4:5], v[148:149] op_sel_hi:[1,0,1] neg_lo:[1,0,0] neg_hi:[1,0,0]
	v_pk_fma_f32 v[48:49], v[44:45], v[48:49], 1.0 op_sel_hi:[1,1,0]
	v_exp_f32_e32 v42, v42
	v_pk_mul_f32 v[48:49], v[44:45], v[48:49] neg_lo:[0,1] neg_hi:[0,1]
	v_exp_f32_e32 v43, v43
	v_cndmask_b32_e32 v44, v50, v48, vcc
	v_cmp_lt_f32_e32 vcc, s7, v45
	v_sqrt_f32_e32 v44, v44
	v_pk_add_f32 v[42:43], v[42:43], 1.0 op_sel_hi:[1,0]
	v_cndmask_b32_e32 v45, v51, v49, vcc
	v_sqrt_f32_e32 v45, v45
	v_rcp_f32_e32 v42, v42
	v_rcp_f32_e32 v43, v43
	v_pk_mul_f32 v[86:87], v[40:41], v[44:45]
	v_pk_fma_f32 v[40:41], v[74:75], s[4:5], v[146:147] op_sel_hi:[1,0,1] neg_lo:[1,0,0] neg_hi:[1,0,0]
	v_pk_mul_f32 v[42:43], v[158:159], v[42:43]
	v_exp_f32_e32 v40, v40
	v_exp_f32_e32 v41, v41
	s_nop 1
v_fmac_f32_dpp v84, v224, v80 row_shl:15 row_mask:0xf bank_mask:0xf
 v_fmac_f32_dpp v85, v225, v81 row_shl:15 row_mask:0xf bank_mask:0xf
v_fmac_f32_dpp v86, v226, v82 row_shl:15 row_mask:0xf bank_mask:0xf
 v_fmac_f32_dpp v87, v227, v83 row_shl:15 row_mask:0xf bank_mask:0xf
v_mul_f32_dpp v80, v220, v80 row_shl:15 row_mask:0xf bank_mask:0xf
 v_mul_f32_dpp v81, v221, v81 row_shl:15 row_mask:0xf bank_mask:0xf
v_mul_f32_dpp v82, v222, v82 row_shl:15 row_mask:0xf bank_mask:0xf
 v_mul_f32_dpp v83, v223, v83 row_shl:15 row_mask:0xf bank_mask:0xf
v_fmac_f32_dpp v84, v84, v80 row_shr:1 row_mask:0xf bank_mask:0xf
 v_fmac_f32_dpp v85, v85, v81 row_shr:1 row_mask:0xf bank_mask:0xf
v_fmac_f32_dpp v86, v86, v82 row_shr:1 row_mask:0xf bank_mask:0xf
 v_fmac_f32_dpp v87, v87, v83 row_shr:1 row_mask:0xf bank_mask:0xf
v_mul_f32_dpp v80, v80, v80 row_shr:1 row_mask:0xf bank_mask:0xf
 v_mul_f32_dpp v81, v81, v81 row_shr:1 row_mask:0xf bank_mask:0xf
v_mul_f32_dpp v82, v82, v82 row_shr:1 row_mask:0xf bank_mask:0xf
 v_mul_f32_dpp v83, v83, v83 row_shr:1 row_mask:0xf bank_mask:0xf
v_fmac_f32_dpp v84, v84, v80 row_shr:2 row_mask:0xf bank_mask:0xf
 v_fmac_f32_dpp v85, v85, v81 row_shr:2 row_mask:0xf bank_mask:0xf
v_fmac_f32_dpp v86, v86, v82 row_shr:2 row_mask:0xf bank_mask:0xf
 v_fmac_f32_dpp v87, v87, v83 row_shr:2 row_mask:0xf bank_mask:0xf
v_mul_f32_dpp v80, v80, v80 row_shr:2 row_mask:0xf bank_mask:0xf
 v_mul_f32_dpp v81, v81, v81 row_shr:2 row_mask:0xf bank_mask:0xf
v_mul_f32_dpp v82, v82, v82 row_shr:2 row_mask:0xf bank_mask:0xf
 v_mul_f32_dpp v83, v83, v83 row_shr:2 row_mask:0xf bank_mask:0xf
v_fmac_f32_dpp v84, v84, v80 row_shr:4 row_mask:0xf bank_mask:0xf
 v_fmac_f32_dpp v85, v85, v81 row_shr:4 row_mask:0xf bank_mask:0xf
v_fmac_f32_dpp v86, v86, v82 row_shr:4 row_mask:0xf bank_mask:0xf
 v_fmac_f32_dpp v87, v87, v83 row_shr:4 row_mask:0xf bank_mask:0xf
v_mul_f32_dpp v80, v80, v80 row_shr:4 row_mask:0xf bank_mask:0xf
 v_mul_f32_dpp v81, v81, v81 row_shr:4 row_mask:0xf bank_mask:0xf
v_mul_f32_dpp v82, v82, v82 row_shr:4 row_mask:0xf bank_mask:0xf
 v_mul_f32_dpp v83, v83, v83 row_shr:4 row_mask:0xf bank_mask:0xf
v_fmac_f32_dpp v84, v84, v80 row_shr:8 row_mask:0xf bank_mask:0xf
 v_fmac_f32_dpp v85, v85, v81 row_shr:8 row_mask:0xf bank_mask:0xf
v_fmac_f32_dpp v86, v86, v82 row_shr:8 row_mask:0xf bank_mask:0xf
 v_fmac_f32_dpp v87, v87, v83 row_shr:8 row_mask:0xf bank_mask:0xf
v_mul_f32_dpp v80, v80, v80 row_shr:8 row_mask:0xf bank_mask:0xf
 v_mul_f32_dpp v81, v81, v81 row_shr:8 row_mask:0xf bank_mask:0xf
v_mul_f32_dpp v82, v82, v82 row_shr:8 row_mask:0xf bank_mask:0xf
 v_mul_f32_dpp v83, v83, v83 row_shr:8 row_mask:0xf bank_mask:0xf
s_nop 1

	v_mov_b32_e32 v238, v97
	v_mov_b32_e32 v228, v92
	v_pk_add_f32 v[40:41], v[40:41], 1.0 op_sel_hi:[1,0]
	v_mov_b32_e32 v229, v96
	v_rcp_f32_e32 v40, v40
	v_rcp_f32_e32 v41, v41
	v_mov_b32_e32 v230, v178
	v_mov_b32_e32 v231, v98
	v_mov_b32_e32 v220, v80
	v_pk_mul_f32 v[40:41], v[150:151], v[40:41]
	v_mov_b32_e32 v221, v81
	v_exp_f32_e32 v70, v40
	v_exp_f32_e32 v71, v41
	v_pk_mul_f32 v[40:41], v[40:41], s[6:7] op_sel_hi:[1,0]
	v_mov_b32_e32 v222, v82
	v_pk_fma_f32 v[44:45], v[40:41], s[0:1], v[38:39] op_sel_hi:[1,0,0]
	v_pk_fma_f32 v[46:47], v[70:71], v[70:71], 1.0 op_sel_hi:[1,1,0] neg_lo:[1,0,0] neg_hi:[1,0,0]
	v_pk_fma_f32 v[44:45], v[40:41], v[44:45], s[8:9] op_sel_hi:[1,1,0]
	v_cmp_lt_f32_e32 vcc, s7, v40
	v_pk_fma_f32 v[44:45], v[40:41], v[44:45], 0.5 op_sel_hi:[1,1,0]
	v_mov_b32_e32 v223, v83
	v_pk_fma_f32 v[44:45], v[40:41], v[44:45], 1.0 op_sel_hi:[1,1,0]
	v_pk_mul_f32 v[44:45], v[40:41], v[44:45] neg_lo:[0,1] neg_hi:[0,1]
	v_cndmask_b32_e32 v40, v46, v44, vcc
	v_cmp_lt_f32_e32 vcc, s7, v41
	v_sqrt_f32_e32 v40, v40
	v_cndmask_b32_e32 v41, v47, v45, vcc
	v_pk_fma_f32 v[44:45], v[76:77], s[4:5], v[152:153] op_sel_hi:[1,0,1] neg_lo:[1,0,0] neg_hi:[1,0,0]
	v_pk_fma_f32 v[46:47], v[72:73], s[4:5], v[154:155] op_sel_hi:[1,0,1] neg_lo:[1,0,0] neg_hi:[1,0,0]
	v_exp_f32_e32 v44, v44
	v_exp_f32_e32 v45, v45
	v_exp_f32_e32 v46, v46
	v_exp_f32_e32 v47, v47
	v_sqrt_f32_e32 v41, v41
	v_pk_add_f32 v[44:45], v[44:45], 1.0 op_sel_hi:[1,0]
	v_rcp_f32_e32 v44, v44
	v_rcp_f32_e32 v45, v45
	v_pk_add_f32 v[46:47], v[46:47], 1.0 op_sel_hi:[1,0]
	v_pk_mul_f32 v[88:89], v[42:43], v[40:41]
	v_rcp_f32_e32 v46, v46
	v_pk_mul_f32 v[44:45], v[156:157], v[44:45]
	v_rcp_f32_e32 v47, v47
	v_exp_f32_e32 v72, v44
	v_exp_f32_e32 v73, v45
	v_pk_mul_f32 v[44:45], v[44:45], s[6:7] op_sel_hi:[1,0]
	v_pk_mul_f32 v[40:41], v[160:161], v[46:47]
	v_pk_fma_f32 v[38:39], v[44:45], s[0:1], v[38:39] op_sel_hi:[1,0,0]
	v_pk_fma_f32 v[48:49], v[72:73], v[72:73], 1.0 op_sel_hi:[1,1,0] neg_lo:[1,0,0] neg_hi:[1,0,0]
	v_pk_fma_f32 v[38:39], v[44:45], v[38:39], s[8:9] op_sel_hi:[1,1,0]
	v_cmp_lt_f32_e32 vcc, s7, v44
	v_pk_fma_f32 v[38:39], v[44:45], v[38:39], 0.5 op_sel_hi:[1,1,0]
	v_mov_b32_e32 v74, v89
	v_pk_fma_f32 v[38:39], v[44:45], v[38:39], 1.0 op_sel_hi:[1,1,0]
	v_readlane_b32 s0, v244, 52
	v_pk_mul_f32 v[38:39], v[44:45], v[38:39] neg_lo:[0,1] neg_hi:[0,1]
	v_readlane_b32 s1, v244, 53
	v_cndmask_b32_e32 v38, v48, v38, vcc
	v_cmp_lt_f32_e32 vcc, s7, v45
	v_sqrt_f32_e32 v38, v38
	v_cndmask_b32_e32 v39, v49, v39, vcc
	v_sqrt_f32_e32 v39, v39
	v_mov_b32_e32 v239, v102
	v_mov_b32_e32 v240, v103
	v_mov_b32_e32 v241, v172
	v_pk_mul_f32 v[90:91], v[40:41], v[38:39]
	v_cvt_pk_bf16_f32 v38, v102, v103
	v_cvt_pk_bf16_f32 v39, v172, v78
	v_cvt_pk_bf16_f32 v40, v79, v99
	v_cvt_pk_bf16_f32 v41, v174, v94
	v_mov_b32_e32 v242, v78
	s_nop 1
v_fmac_f32_dpp v88, v216, v70 row_shl:15 row_mask:0xf bank_mask:0xf
 v_fmac_f32_dpp v74, v217, v71 row_shl:15 row_mask:0xf bank_mask:0xf
v_fmac_f32_dpp v90, v218, v72 row_shl:15 row_mask:0xf bank_mask:0xf
 v_fmac_f32_dpp v91, v219, v73 row_shl:15 row_mask:0xf bank_mask:0xf
v_mul_f32_dpp v70, v171, v70 row_shl:15 row_mask:0xf bank_mask:0xf
 v_mul_f32_dpp v71, v213, v71 row_shl:15 row_mask:0xf bank_mask:0xf
v_mul_f32_dpp v72, v214, v72 row_shl:15 row_mask:0xf bank_mask:0xf
 v_mul_f32_dpp v73, v215, v73 row_shl:15 row_mask:0xf bank_mask:0xf
v_fmac_f32_dpp v88, v88, v70 row_shr:1 row_mask:0xf bank_mask:0xf
 v_fmac_f32_dpp v74, v74, v71 row_shr:1 row_mask:0xf bank_mask:0xf
v_fmac_f32_dpp v90, v90, v72 row_shr:1 row_mask:0xf bank_mask:0xf
 v_fmac_f32_dpp v91, v91, v73 row_shr:1 row_mask:0xf bank_mask:0xf
v_mul_f32_dpp v70, v70, v70 row_shr:1 row_mask:0xf bank_mask:0xf
 v_mul_f32_dpp v71, v71, v71 row_shr:1 row_mask:0xf bank_mask:0xf
v_mul_f32_dpp v72, v72, v72 row_shr:1 row_mask:0xf bank_mask:0xf
 v_mul_f32_dpp v73, v73, v73 row_shr:1 row_mask:0xf bank_mask:0xf
v_fmac_f32_dpp v88, v88, v70 row_shr:2 row_mask:0xf bank_mask:0xf
 v_fmac_f32_dpp v74, v74, v71 row_shr:2 row_mask:0xf bank_mask:0xf
v_fmac_f32_dpp v90, v90, v72 row_shr:2 row_mask:0xf bank_mask:0xf
 v_fmac_f32_dpp v91, v91, v73 row_shr:2 row_mask:0xf bank_mask:0xf
v_mul_f32_dpp v70, v70, v70 row_shr:2 row_mask:0xf bank_mask:0xf
 v_mul_f32_dpp v71, v71, v71 row_shr:2 row_mask:0xf bank_mask:0xf
v_mul_f32_dpp v72, v72, v72 row_shr:2 row_mask:0xf bank_mask:0xf
 v_mul_f32_dpp v73, v73, v73 row_shr:2 row_mask:0xf bank_mask:0xf
v_fmac_f32_dpp v88, v88, v70 row_shr:4 row_mask:0xf bank_mask:0xf
 v_fmac_f32_dpp v74, v74, v71 row_shr:4 row_mask:0xf bank_mask:0xf
v_fmac_f32_dpp v90, v90, v72 row_shr:4 row_mask:0xf bank_mask:0xf
 v_fmac_f32_dpp v91, v91, v73 row_shr:4 row_mask:0xf bank_mask:0xf
v_mul_f32_dpp v70, v70, v70 row_shr:4 row_mask:0xf bank_mask:0xf
 v_mul_f32_dpp v71, v71, v71 row_shr:4 row_mask:0xf bank_mask:0xf
v_mul_f32_dpp v72, v72, v72 row_shr:4 row_mask:0xf bank_mask:0xf
 v_mul_f32_dpp v73, v73, v73 row_shr:4 row_mask:0xf bank_mask:0xf
v_fmac_f32_dpp v88, v88, v70 row_shr:8 row_mask:0xf bank_mask:0xf
 v_fmac_f32_dpp v74, v74, v71 row_shr:8 row_mask:0xf bank_mask:0xf
v_fmac_f32_dpp v90, v90, v72 row_shr:8 row_mask:0xf bank_mask:0xf
 v_fmac_f32_dpp v91, v91, v73 row_shr:8 row_mask:0xf bank_mask:0xf
v_mul_f32_dpp v70, v70, v70 row_shr:8 row_mask:0xf bank_mask:0xf
 v_mul_f32_dpp v71, v71, v71 row_shr:8 row_mask:0xf bank_mask:0xf
v_mul_f32_dpp v72, v72, v72 row_shr:8 row_mask:0xf bank_mask:0xf
 v_mul_f32_dpp v73, v73, v73 row_shr:8 row_mask:0xf bank_mask:0xf
s_nop 1

	v_ashrrev_i32_e32 v171, 31, v170
	v_lshlrev_b64 v[42:43], 10, v[170:171]
	v_lshl_add_u64 v[44:45], s[0:1], 0, v[42:43]
	v_readlane_b32 s0, v244, 54
	v_lshl_add_u64 v[46:47], v[44:45], 0, v[166:167]
	v_readlane_b32 s1, v244, 55
	global_store_dwordx4 v[46:47], v[38:41], off
	v_lshl_add_u64 v[44:45], v[44:45], 0, v[164:165]
	v_lshl_add_u64 v[42:43], s[0:1], 0, v[42:43]
	v_cvt_pk_bf16_f32 v38, v84, v85
	v_cvt_pk_bf16_f32 v39, v86, v87
	v_cvt_pk_bf16_f32 v40, v88, v74
	v_cvt_pk_bf16_f32 v41, v90, v91
	global_store_dwordx4 v[44:45], v[38:41], off
	v_lshl_add_u64 v[44:45], v[42:43], 0, v[166:167]
	v_lshl_add_u64 v[42:43], v[42:43], 0, v[164:165]
	v_cvt_pk_bf16_f32 v38, v100, v4
	v_cvt_pk_bf16_f32 v39, v5, v97
	v_cvt_pk_bf16_f32 v40, v92, v96
	v_cvt_pk_bf16_f32 v41, v178, v98
	global_store_dwordx4 v[44:45], v[38:41], off
	v_mov_b32_e32 v171, v70
	v_cvt_pk_bf16_f32 v38, v80, v81
	v_cvt_pk_bf16_f32 v39, v82, v83
	v_cvt_pk_bf16_f32 v40, v70, v71
	v_cvt_pk_bf16_f32 v41, v72, v73
	global_store_dwordx4 v[42:43], v[38:41], off
	v_mov_b32_e32 v213, v71
	v_mov_b32_e32 v214, v72
	v_mov_b32_e32 v215, v73
	v_mov_b32_e32 v232, v79
	v_mov_b32_e32 v233, v99
	v_mov_b32_e32 v234, v174
	v_mov_b32_e32 v235, v94
	v_mov_b32_e32 v224, v84
	v_mov_b32_e32 v225, v85
	v_mov_b32_e32 v226, v86
	v_mov_b32_e32 v227, v87
	v_mov_b32_e32 v216, v88
	v_mov_b32_e32 v217, v74
	v_mov_b32_e32 v218, v90
	v_mov_b32_e32 v219, v91
	s_cbranch_scc1 .LBB0_227
.LBB0_223:
	ds_read_b128 v[66:69], v2
	ds_read_b32 v4, v2 offset:16
	ds_read_b128 v[70:73], v196
	ds_read_b32 v5, v196 offset:16
	ds_read_b128 v[54:57], v197
	ds_read_b32 v78, v197 offset:16
	ds_read_b128 v[58:61], v198
	ds_read_b32 v79, v198 offset:16
	ds_read_b128 v[46:49], v199
	ds_read_b32 v82, v199 offset:16
	ds_read_b128 v[50:53], v200
	ds_read_b32 v83, v200 offset:16
	ds_read_b128 v[38:41], v201
	ds_read_b32 v76, v201 offset:16
	ds_read_b128 v[42:45], v202
	ds_read_b32 v77, v202 offset:16
	ds_read_b128 v[62:65], v203
	ds_read_b32 v86, v203 offset:16
	ds_read_b32 v87, v204 offset:16
	ds_read_b32 v84, v205 offset:16
	ds_read_b32 v85, v206 offset:16
	ds_read_b32 v80, v207 offset:16
	ds_read_b32 v81, v208 offset:16
	ds_read_b32 v74, v209 offset:16
	ds_read_b32 v75, v210 offset:16
	s_waitcnt vmcnt(4)
	v_lshlrev_b32_e32 v92, 16, v14
	v_and_b32_e32 v93, 0xffff0000, v14
	s_waitcnt lgkmcnt(14)
	v_mov_b32_e32 v94, v66
	v_mov_b32_e32 v95, v70
	v_pk_fma_f32 v[4:5], v[94:95], v[92:93], v[4:5]
	v_lshlrev_b32_e32 v92, 16, v18
	v_and_b32_e32 v93, 0xffff0000, v18
	v_mov_b32_e32 v70, v67
	v_pk_fma_f32 v[4:5], v[70:71], v[92:93], v[4:5]
	v_lshlrev_b32_e32 v66, 16, v22
	v_and_b32_e32 v67, 0xffff0000, v22
	v_mov_b32_e32 v70, v68
	v_mov_b32_e32 v71, v72
	v_pk_fma_f32 v[4:5], v[70:71], v[66:67], v[4:5]
	v_lshlrev_b32_e32 v66, 16, v34
	v_and_b32_e32 v67, 0xffff0000, v34
	v_mov_b32_e32 v72, v69
	v_pk_fma_f32 v[4:5], v[72:73], v[66:67], v[4:5]
	ds_read_b128 v[66:69], v2 offset:1056
	ds_read_b128 v[70:73], v2 offset:1088
	v_lshlrev_b32_e32 v92, 16, v10
	v_and_b32_e32 v93, 0xffff0000, v10
	s_waitcnt lgkmcnt(10)
	v_mov_b32_e32 v94, v62
	s_waitcnt lgkmcnt(1)
	v_mov_b32_e32 v95, v66
	v_pk_fma_f32 v[86:87], v[94:95], v[92:93], v[86:87]
	v_lshlrev_b32_e32 v92, 16, v6
	v_and_b32_e32 v93, 0xffff0000, v6
	v_mov_b32_e32 v66, v63
	v_pk_fma_f32 v[62:63], v[66:67], v[92:93], v[86:87]
	v_lshlrev_b32_e32 v66, 16, v26
	v_and_b32_e32 v67, 0xffff0000, v26
	v_mov_b32_e32 v86, v64
	v_mov_b32_e32 v87, v68
	v_pk_fma_f32 v[62:63], v[86:87], v[66:67], v[62:63]
	v_lshlrev_b32_e32 v66, 16, v30
	v_and_b32_e32 v67, 0xffff0000, v30
	v_mov_b32_e32 v68, v65
	v_pk_fma_f32 v[162:163], v[68:69], v[66:67], v[62:63]
	v_lshlrev_b32_e32 v62, 16, v15
	v_and_b32_e32 v63, 0xffff0000, v15
	v_mov_b32_e32 v64, v54
	v_mov_b32_e32 v65, v58
	v_pk_fma_f32 v[62:63], v[64:65], v[62:63], v[78:79]
	v_lshlrev_b32_e32 v64, 16, v19
	v_and_b32_e32 v65, 0xffff0000, v19
	v_mov_b32_e32 v58, v55
	v_pk_fma_f32 v[54:55], v[58:59], v[64:65], v[62:63]
	v_lshlrev_b32_e32 v58, 16, v23
	v_and_b32_e32 v59, 0xffff0000, v23
	v_mov_b32_e32 v62, v56
	v_mov_b32_e32 v63, v60
	v_pk_fma_f32 v[54:55], v[62:63], v[58:59], v[54:55]
	v_lshlrev_b32_e32 v58, 16, v35
	v_and_b32_e32 v59, 0xffff0000, v35
	v_mov_b32_e32 v60, v57
	v_pk_fma_f32 v[78:79], v[60:61], v[58:59], v[54:55]
	ds_read_b128 v[54:57], v2 offset:1120
	ds_read_b128 v[58:61], v2 offset:1152
	v_lshlrev_b32_e32 v62, 16, v11
	v_and_b32_e32 v63, 0xffff0000, v11
	s_waitcnt lgkmcnt(2)
	v_mov_b32_e32 v64, v70
	s_waitcnt lgkmcnt(1)
	v_mov_b32_e32 v65, v54
	v_pk_fma_f32 v[62:63], v[64:65], v[62:63], v[84:85]
	v_lshlrev_b32_e32 v64, 16, v7
	v_and_b32_e32 v65, 0xffff0000, v7
	v_mov_b32_e32 v54, v71
	v_pk_fma_f32 v[54:55], v[54:55], v[64:65], v[62:63]
	v_lshlrev_b32_e32 v62, 16, v27
	v_and_b32_e32 v63, 0xffff0000, v27
	v_mov_b32_e32 v64, v72
	v_mov_b32_e32 v65, v56
	v_pk_fma_f32 v[54:55], v[64:65], v[62:63], v[54:55]
	v_lshlrev_b32_e32 v62, 16, v31
	v_and_b32_e32 v63, 0xffff0000, v31
	v_mov_b32_e32 v56, v73
	v_pk_fma_f32 v[168:169], v[56:57], v[62:63], v[54:55]
	v_lshlrev_b32_e32 v54, 16, v16
	v_and_b32_e32 v55, 0xffff0000, v16
	v_mov_b32_e32 v56, v46
	v_mov_b32_e32 v57, v50
	v_pk_fma_f32 v[54:55], v[56:57], v[54:55], v[82:83]
	v_lshlrev_b32_e32 v56, 16, v20
	v_and_b32_e32 v57, 0xffff0000, v20
	v_mov_b32_e32 v50, v47
	v_pk_fma_f32 v[46:47], v[50:51], v[56:57], v[54:55]
	v_lshlrev_b32_e32 v50, 16, v24
	v_and_b32_e32 v51, 0xffff0000, v24
	v_mov_b32_e32 v54, v48
	v_mov_b32_e32 v55, v52
	v_pk_fma_f32 v[46:47], v[54:55], v[50:51], v[46:47]
	v_lshlrev_b32_e32 v50, 16, v36
	v_and_b32_e32 v51, 0xffff0000, v36
	v_mov_b32_e32 v52, v49
	v_pk_fma_f32 v[174:175], v[52:53], v[50:51], v[46:47]
	ds_read_b128 v[46:49], v2 offset:1184
	ds_read_b128 v[50:53], v2 offset:1216
	v_lshlrev_b32_e32 v54, 16, v12
	v_and_b32_e32 v55, 0xffff0000, v12
	s_waitcnt lgkmcnt(2)
	v_mov_b32_e32 v56, v58
	s_waitcnt lgkmcnt(1)
	v_mov_b32_e32 v57, v46
	v_pk_fma_f32 v[54:55], v[56:57], v[54:55], v[80:81]
	v_lshlrev_b32_e32 v56, 16, v8
	v_and_b32_e32 v57, 0xffff0000, v8
	v_mov_b32_e32 v46, v59
	v_pk_fma_f32 v[46:47], v[46:47], v[56:57], v[54:55]
	v_lshlrev_b32_e32 v54, 16, v28
	v_and_b32_e32 v55, 0xffff0000, v28
	v_mov_b32_e32 v56, v60
	v_mov_b32_e32 v57, v48
	ds_read_b128 v[88:91], v2 offset:1248
	v_pk_fma_f32 v[46:47], v[56:57], v[54:55], v[46:47]
	v_lshlrev_b32_e32 v54, 16, v32
	v_and_b32_e32 v55, 0xffff0000, v32
	v_mov_b32_e32 v48, v61
	v_pk_fma_f32 v[158:159], v[48:49], v[54:55], v[46:47]
	v_lshlrev_b32_e32 v46, 16, v17
	v_and_b32_e32 v47, 0xffff0000, v17
	v_mov_b32_e32 v48, v38
	v_mov_b32_e32 v49, v42
	v_pk_fma_f32 v[46:47], v[48:49], v[46:47], v[76:77]
	v_lshlrev_b32_e32 v48, 16, v21
	v_and_b32_e32 v49, 0xffff0000, v21
	v_mov_b32_e32 v42, v39
	v_pk_fma_f32 v[38:39], v[42:43], v[48:49], v[46:47]
	v_lshlrev_b32_e32 v42, 16, v25
	v_and_b32_e32 v43, 0xffff0000, v25
	v_mov_b32_e32 v46, v40
	v_mov_b32_e32 v47, v44
	v_pk_fma_f32 v[38:39], v[46:47], v[42:43], v[38:39]
	v_lshlrev_b32_e32 v42, 16, v37
	v_and_b32_e32 v43, 0xffff0000, v37
	v_mov_b32_e32 v44, v41
	v_pk_fma_f32 v[176:177], v[44:45], v[42:43], v[38:39]
	v_lshlrev_b32_e32 v38, 16, v13
	v_and_b32_e32 v39, 0xffff0000, v13
	s_waitcnt lgkmcnt(1)
	v_mov_b32_e32 v40, v50
	ds_read_b128 v[46:49], v211 offset:24576
	s_waitcnt lgkmcnt(1)
	v_mov_b32_e32 v41, v88
	v_pk_fma_f32 v[38:39], v[40:41], v[38:39], v[74:75]
	v_lshlrev_b32_e32 v40, 16, v9
	v_and_b32_e32 v41, 0xffff0000, v9
	v_mov_b32_e32 v88, v51
	v_pk_fma_f32 v[38:39], v[88:89], v[40:41], v[38:39]
	v_lshlrev_b32_e32 v40, 16, v29
	v_and_b32_e32 v41, 0xffff0000, v29
	v_mov_b32_e32 v42, v52
	v_mov_b32_e32 v43, v90
	v_pk_fma_f32 v[42:43], v[42:43], v[40:41], v[38:39]
	ds_read_b128 v[38:41], v211 offset:16384
	v_lshlrev_b32_e32 v44, 16, v33
	v_and_b32_e32 v45, 0xffff0000, v33
	v_mov_b32_e32 v90, v53
	ds_read_b128 v[50:53], v212 offset:16384
	ds_read_b128 v[54:57], v211 offset:16896
	ds_read_b128 v[62:65], v211 offset:25088
	ds_read_b128 v[66:69], v212 offset:16896
	v_pk_fma_f32 v[160:161], v[90:91], v[44:45], v[42:43]
	s_cmpk_eq_i32 s2, 0x70
	s_cbranch_scc1 .Llru_noload
	v_add3_u32 v248, v113, s2, 13
	v_mul_u32_u24_e32 v248, 0x1200, v248
	v_lshl_add_u32 v248, v104, 1, v248
	v_add_u32_e32 v249, 0x1200, v248
	v_add_u32_e32 v250, 0x2400, v248
	v_add_u32_e32 v251, 0x3600, v248
	global_load_dwordx4 v[14:17], v248, s[88:89]
	global_load_dwordx4 v[10:13], v248, s[88:89] offset:64
	global_load_dwordx4 v[18:21], v249, s[88:89]
	global_load_dwordx4 v[6:9], v249, s[88:89] offset:64
	global_load_dwordx4 v[22:25], v250, s[88:89]
	global_load_dwordx4 v[26:29], v250, s[88:89] offset:64
	global_load_dwordx4 v[34:37], v251, s[88:89]
	global_load_dwordx4 v[30:33], v251, s[88:89] offset:64
.Llru_noload:
	v_cvt_pk_bf16_f32 v42, v4, v5
	v_cvt_pk_bf16_f32 v43, v78, v79
	v_cvt_pk_bf16_f32 v44, v174, v175
	v_cvt_pk_bf16_f32 v45, v176, v177
	v_cvt_pk_bf16_f32 v58, v162, v163
	v_cvt_pk_bf16_f32 v59, v168, v169
	v_cvt_pk_bf16_f32 v60, v158, v159
	s_nop 0
	v_cvt_pk_bf16_f32 v61, v160, v161
	s_mov_b64 s[0:1], -1
	s_waitcnt lgkmcnt(4)
	v_mfma_f32_16x16x32_bf16 v[38:41], v[38:41], v[42:45], 0
	v_lshlrev_b64 v[166:167], 1, v[104:105]
	v_lshlrev_b64 v[164:165], 1, v[106:107]
	v_mfma_f32_16x16x32_bf16 v[46:49], v[46:49], v[42:45], 0
	v_add_u32_e32 v172, s2, v113
	s_waitcnt lgkmcnt(3)
	v_mfma_f32_16x16x32_bf16 v[100:103], v[50:53], v[58:61], v[38:41]
	s_nop 2
	ds_read_b128 v[38:41], v212 offset:24576
	ds_read_b128 v[50:53], v212 offset:25088
	s_waitcnt lgkmcnt(1)
	v_mfma_f32_16x16x32_bf16 v[96:99], v[38:41], v[58:61], v[46:49]
	v_mfma_f32_16x16x32_bf16 v[38:41], v[54:57], v[42:45], 0
	v_mfma_f32_16x16x32_bf16 v[46:49], v[62:65], v[42:45], 0
	v_mfma_f32_16x16x32_bf16 v[92:95], v[66:69], v[58:61], v[38:41]
	s_waitcnt lgkmcnt(0)
	v_mfma_f32_16x16x32_bf16 v[88:91], v[50:53], v[58:61], v[46:49]
	s_nop 3
	ds_read_b128 v[38:41], v211 offset:20480
	ds_read_b128 v[46:49], v211 offset:20992
	ds_read_b128 v[50:53], v211 offset:28672
	ds_read_b128 v[54:57], v211 offset:29184
	ds_read_b128 v[62:65], v212 offset:20480
	ds_read_b128 v[66:69], v212 offset:20992
	s_waitcnt lgkmcnt(5)
	v_mfma_f32_16x16x32_bf16 v[38:41], v[38:41], v[42:45], 0
	s_waitcnt lgkmcnt(3)
	v_mfma_f32_16x16x32_bf16 v[50:53], v[50:53], v[42:45], 0
	s_waitcnt lgkmcnt(1)
	v_mfma_f32_16x16x32_bf16 v[84:87], v[62:65], v[58:61], v[38:41]
	s_nop 3
	ds_read_b128 v[38:41], v212 offset:28672
	ds_read_b128 v[62:65], v212 offset:29184
	s_waitcnt lgkmcnt(1)
	v_mfma_f32_16x16x32_bf16 v[80:83], v[38:41], v[58:61], v[50:53]
	v_mfma_f32_16x16x32_bf16 v[38:41], v[46:49], v[42:45], 0
	v_mfma_f32_16x16x32_bf16 v[42:45], v[54:57], v[42:45], 0
	v_mfma_f32_16x16x32_bf16 v[74:77], v[66:69], v[58:61], v[38:41]
	s_waitcnt lgkmcnt(0)
	v_mfma_f32_16x16x32_bf16 v[70:73], v[62:65], v[58:61], v[42:45]
	v_add_u32_e32 v170, s2, v113
	s_branch .LBB0_222
